# v3: K-loop A-stage rebalance (6 loops) + ssq loads of P4/P11 epilogues issued together + pass C tile loads issued together (one wait)
# speedup vs baseline: 1.0101x; 1.0035x over previous
;     __device__ __forceinline__ void operator()(const f32x4 (&acc)[2][2][4][2], const Unit& u, int wr, int wc, int fr, int fq) const {
;         const int row0 = u.pm * BM + wr * 64 + fr, colt = u.pn * BM, col0 = colt + wc * 32 + 8 * fq;
;         const int mode = (colt >= PC_GA || (colt >= PC_MO && colt < PC_SQ)) ? 1 : ((colt >= PC_SQ && colt < PC_SK) ? 2 : 0);
; #pragma unroll
;         for (int ai = 0; ai < 2; ++ai)
; #pragma unroll
;             for (int m = 0; m < 4; ++m) { const int row = row0 + ai * HALF + m * 16; bf16_t* rowp = O + (size_t)row * ldc + col0;
;                 const float rs = 1.0f / sqrtf(ssq[row] * (1.0f / D) + RMS_EPS);
; #pragma unroll
;                 for (int bj = 0; bj < 2; ++bj) { f32x4 v0 = acc[ai][bj][m][0] * rs, v1 = acc[ai][bj][m][1] * rs;
.LBB0_293:
	v_lshl_add_u32 v146, s4, 8, v1
	v_ashrrev_i32_e32 v147, 31, v146
	v_lshl_add_u64 v[148:149], v[146:147], 2, s[10:11]
	global_load_dword v147, v[148:149], off
	global_load_dword v168, v[148:149], off offset:64
	global_load_dword v169, v[148:149], off offset:128
	global_load_dword v170, v[148:149], off offset:192
	global_load_dword v171, v[148:149], off offset:512
	global_load_dword v172, v[148:149], off offset:576
	global_load_dword v173, v[148:149], off offset:640
	global_load_dword v174, v[148:149], off offset:704
	s_cmp_gt_i32 s50, 47
	s_cselect_b64 s[4:5], -1, 0
	s_and_b32 s17, s50, -8
	s_cmp_eq_u32 s17, 16
	s_cselect_b64 s[58:59], -1, 0
	s_or_b64 s[4:5], s[4:5], s[58:59]
	s_cmp_eq_u32 s17, 24
	s_cselect_b32 s17, 2, 0
	s_and_b64 s[4:5], s[4:5], exec
	s_cselect_b32 s17, 1, s17
	s_cmp_gt_i32 s17, 1
	s_waitcnt vmcnt(0)
	v_fmamk_f32 v147, v147, 0x39800000, v165
	v_mul_f32_e32 v150, 0x4f800000, v147
	v_cmp_gt_f32_e32 vcc, s83, v147
	s_nop 1
	v_cndmask_b32_e32 v147, v147, v150, vcc
	v_sqrt_f32_e32 v150, v147
	s_nop 0
	v_add_u32_e32 v151, -1, v150
	v_add_u32_e32 v152, 1, v150
	v_fma_f32 v153, -v151, v150, v147
	v_fma_f32 v154, -v152, v150, v147
	v_cmp_ge_f32_e64 s[4:5], 0, v153
	s_nop 1
	v_cndmask_b32_e64 v150, v150, v151, s[4:5]
	v_cmp_lt_f32_e64 s[4:5], 0, v154
	s_nop 1
	v_cndmask_b32_e64 v150, v150, v152, s[4:5]
	v_mul_f32_e32 v151, 0x37800000, v150
	v_cndmask_b32_e32 v150, v150, v151, vcc
	v_cmp_class_f32_e32 vcc, v147, v166
	s_nop 1
	v_cndmask_b32_e32 v147, v150, v147, vcc
	v_div_scale_f32 v150, s[4:5], v147, v147, 1.0
	v_rcp_f32_e32 v151, v150
	v_div_scale_f32 v152, vcc, 1.0, v147, 1.0
	s_mov_b64 s[4:5], -1
	v_fma_f32 v153, -v150, v151, 1.0
	v_fmac_f32_e32 v151, v153, v151
	v_mul_f32_e32 v153, v152, v151
	v_fma_f32 v154, -v150, v153, v152
	v_fmac_f32_e32 v153, v154, v151
	v_fma_f32 v150, -v150, v153, v152
	v_div_fmas_f32 v150, v150, v151, v153
	v_div_fixup_f32 v150, v150, v147, 1.0
	v_pk_mul_f32 v[128:129], v[128:129], v[150:151] op_sel_hi:[1,0]
	v_pk_mul_f32 v[126:127], v[126:127], v[150:151] op_sel_hi:[1,0]
	v_pk_mul_f32 v[124:125], v[124:125], v[150:151] op_sel_hi:[1,0]
	v_pk_mul_f32 v[122:123], v[122:123], v[150:151] op_sel_hi:[1,0]
	s_cbranch_scc0 .LBB0_295
	v_pk_mul_f32 v[152:153], v[128:129], s[14:15] op_sel_hi:[1,0]
	v_pk_mul_f32 v[156:157], v[126:127], s[14:15] op_sel_hi:[1,0]
	v_pk_mul_f32 v[154:155], v[124:125], s[14:15] op_sel_hi:[1,0]
	v_pk_mul_f32 v[158:159], v[122:123], s[14:15] op_sel_hi:[1,0]
	s_mov_b64 s[4:5], 0

; __device__ __forceinline__ unsigned pk2(float lo, float hi) { f32x2 v = {lo, hi}; bf16x2_t b = __builtin_convertvector(v, bf16x2_t); return __builtin_bit_cast(unsigned, b); }
; __device__ __forceinline__ float fsigmoid(float x) { return __builtin_amdgcn_rcpf(1.0f + __expf(-x)); }
;     __device__ __forceinline__ void operator()(const f32x4 (&acc)[2][2][4][2], const Unit& u, int wr, int wc, int fr, int fq) const {
;     ...
;             for (int m = 0; m < 4; ++m) { const int row = row0 + ai * HALF + m * 16; bf16_t* rowp = O + (size_t)row * ldc + col0;
;                 const float rs = 1.0f / sqrtf(ssq[row] * (1.0f / D) + RMS_EPS);
; #pragma unroll
;                 for (int bj = 0; bj < 2; ++bj) { f32x4 v0 = acc[ai][bj][m][0] * rs, v1 = acc[ai][bj][m][1] * rs;
;                     if (mode == 1) {
; #pragma unroll
;                         for (int j = 0; j < 4; ++j) { v0[j] = fsigmoid(v0[j]); v1[j] = fsigmoid(v1[j]); } }
;                     else if (mode == 2) { v0 = v0 * 0.08838834764831845f; v1 = v1 * 0.08838834764831845f; }
;                     u32x4 w; w.x = pk2(v0[0], v0[1]); w.y = pk2(v0[2], v0[3]); w.z = pk2(v1[0], v1[1]); w.w = pk2(v1[2], v1[3]);
;                     *(u32x4*)(rowp + bj * HALF) = w; } }
.LBB0_305:
	v_cvt_pk_bf16_f32 v114, v150, v151
	v_cvt_pk_bf16_f32 v115, v126, v127
	v_cvt_pk_bf16_f32 v116, v152, v153
	v_cvt_pk_bf16_f32 v117, v128, v129
	global_store_dwordx4 v[124:125], v[114:117], off offset:256
	s_cmp_gt_i32 s17, 1
	s_nop 0
	v_or_b32_e32 v114, 16, v146
	v_ashrrev_i32_e32 v115, 31, v114
	v_lshl_add_u64 v[116:117], v[114:115], 2, s[10:11]
	s_nop 0
	v_mov_b32_e32 v115, v168
	v_fmamk_f32 v115, v115, 0x39800000, v165
	v_mul_f32_e32 v116, 0x4f800000, v115
	v_cmp_gt_f32_e32 vcc, s83, v115
	s_nop 1
	v_cndmask_b32_e32 v115, v115, v116, vcc
	v_sqrt_f32_e32 v116, v115
	s_nop 0
	v_add_u32_e32 v117, -1, v116
	v_add_u32_e32 v118, 1, v116
	v_fma_f32 v119, -v117, v116, v115
	v_fma_f32 v120, -v118, v116, v115
	v_cmp_ge_f32_e64 s[4:5], 0, v119
	s_nop 1
	v_cndmask_b32_e64 v116, v116, v117, s[4:5]
	v_cmp_lt_f32_e64 s[4:5], 0, v120
	s_nop 1
	v_cndmask_b32_e64 v116, v116, v118, s[4:5]
	v_mul_f32_e32 v117, 0x37800000, v116
	v_cndmask_b32_e32 v116, v116, v117, vcc
	v_cmp_class_f32_e32 vcc, v115, v166
	s_nop 1
	v_cndmask_b32_e32 v115, v116, v115, vcc
	v_div_scale_f32 v116, s[4:5], v115, v115, 1.0
	v_rcp_f32_e32 v117, v116
	v_div_scale_f32 v118, vcc, 1.0, v115, 1.0
	s_mov_b64 s[4:5], -1
	v_fma_f32 v119, -v116, v117, 1.0
	v_fmac_f32_e32 v117, v119, v117
	v_mul_f32_e32 v119, v118, v117
	v_fma_f32 v120, -v116, v119, v118
	v_fmac_f32_e32 v119, v120, v117
	v_fma_f32 v116, -v116, v119, v118
	v_div_fmas_f32 v116, v116, v117, v119
	v_div_fixup_f32 v116, v116, v115, 1.0
	v_pk_mul_f32 v[112:113], v[112:113], v[116:117] op_sel_hi:[1,0]
	v_pk_mul_f32 v[110:111], v[110:111], v[116:117] op_sel_hi:[1,0]
	v_pk_mul_f32 v[108:109], v[108:109], v[116:117] op_sel_hi:[1,0]
	v_pk_mul_f32 v[106:107], v[106:107], v[116:117] op_sel_hi:[1,0]
	s_cbranch_scc0 .LBB0_307
	v_pk_mul_f32 v[118:119], v[112:113], s[14:15] op_sel_hi:[1,0]
	v_pk_mul_f32 v[124:125], v[110:111], s[14:15] op_sel_hi:[1,0]
	v_pk_mul_f32 v[120:121], v[108:109], s[14:15] op_sel_hi:[1,0]
	v_pk_mul_f32 v[126:127], v[106:107], s[14:15] op_sel_hi:[1,0]
	s_mov_b64 s[4:5], 0

; __device__ __forceinline__ unsigned pk2(float lo, float hi) { f32x2 v = {lo, hi}; bf16x2_t b = __builtin_convertvector(v, bf16x2_t); return __builtin_bit_cast(unsigned, b); }
; __device__ __forceinline__ float fsigmoid(float x) { return __builtin_amdgcn_rcpf(1.0f + __expf(-x)); }
;     __device__ __forceinline__ void operator()(const f32x4 (&acc)[2][2][4][2], const Unit& u, int wr, int wc, int fr, int fq) const {
;     ...
;             for (int m = 0; m < 4; ++m) { const int row = row0 + ai * HALF + m * 16; bf16_t* rowp = O + (size_t)row * ldc + col0;
;                 const float rs = 1.0f / sqrtf(ssq[row] * (1.0f / D) + RMS_EPS);
; #pragma unroll
;                 for (int bj = 0; bj < 2; ++bj) { f32x4 v0 = acc[ai][bj][m][0] * rs, v1 = acc[ai][bj][m][1] * rs;
;                     if (mode == 1) {
; #pragma unroll
;                         for (int j = 0; j < 4; ++j) { v0[j] = fsigmoid(v0[j]); v1[j] = fsigmoid(v1[j]); } }
;                     else if (mode == 2) { v0 = v0 * 0.08838834764831845f; v1 = v1 * 0.08838834764831845f; }
;                     u32x4 w; w.x = pk2(v0[0], v0[1]); w.y = pk2(v0[2], v0[3]); w.z = pk2(v1[0], v1[1]); w.w = pk2(v1[2], v1[3]);
;                     *(u32x4*)(rowp + bj * HALF) = w; } }
.LBB0_317:
	v_cvt_pk_bf16_f32 v98, v112, v113
	v_cvt_pk_bf16_f32 v99, v108, v109
	v_cvt_pk_bf16_f32 v100, v114, v115
	v_cvt_pk_bf16_f32 v101, v110, v111
	global_store_dwordx4 v[106:107], v[98:101], off offset:256
	s_cmp_gt_i32 s17, 1
	s_nop 0
	v_or_b32_e32 v98, 32, v146
	v_ashrrev_i32_e32 v99, 31, v98
	v_lshl_add_u64 v[100:101], v[98:99], 2, s[10:11]
	s_nop 0
	v_mov_b32_e32 v99, v169
	v_fmamk_f32 v99, v99, 0x39800000, v165
	v_mul_f32_e32 v100, 0x4f800000, v99
	v_cmp_gt_f32_e32 vcc, s83, v99
	s_nop 1
	v_cndmask_b32_e32 v99, v99, v100, vcc
	v_sqrt_f32_e32 v100, v99
	s_nop 0
	v_add_u32_e32 v101, -1, v100
	v_add_u32_e32 v102, 1, v100
	v_fma_f32 v103, -v101, v100, v99
	v_fma_f32 v104, -v102, v100, v99
	v_cmp_ge_f32_e64 s[4:5], 0, v103
	s_nop 1
	v_cndmask_b32_e64 v100, v100, v101, s[4:5]
	v_cmp_lt_f32_e64 s[4:5], 0, v104
	s_nop 1
	v_cndmask_b32_e64 v100, v100, v102, s[4:5]
	v_mul_f32_e32 v101, 0x37800000, v100
	v_cndmask_b32_e32 v100, v100, v101, vcc
	v_cmp_class_f32_e32 vcc, v99, v166
	s_nop 1
	v_cndmask_b32_e32 v99, v100, v99, vcc
	v_div_scale_f32 v100, s[4:5], v99, v99, 1.0
	v_rcp_f32_e32 v101, v100
	v_div_scale_f32 v102, vcc, 1.0, v99, 1.0
	s_mov_b64 s[4:5], -1
	v_fma_f32 v103, -v100, v101, 1.0
	v_fmac_f32_e32 v101, v103, v101
	v_mul_f32_e32 v103, v102, v101
	v_fma_f32 v104, -v100, v103, v102
	v_fmac_f32_e32 v103, v104, v101
	v_fma_f32 v100, -v100, v103, v102
	v_div_fmas_f32 v100, v100, v101, v103
	v_div_fixup_f32 v100, v100, v99, 1.0
	v_pk_mul_f32 v[96:97], v[96:97], v[100:101] op_sel_hi:[1,0]
	v_pk_mul_f32 v[94:95], v[94:95], v[100:101] op_sel_hi:[1,0]
	v_pk_mul_f32 v[92:93], v[92:93], v[100:101] op_sel_hi:[1,0]
	v_pk_mul_f32 v[90:91], v[90:91], v[100:101] op_sel_hi:[1,0]
	s_cbranch_scc0 .LBB0_319
	v_pk_mul_f32 v[102:103], v[96:97], s[14:15] op_sel_hi:[1,0]
	v_pk_mul_f32 v[106:107], v[94:95], s[14:15] op_sel_hi:[1,0]
	v_pk_mul_f32 v[104:105], v[92:93], s[14:15] op_sel_hi:[1,0]
	v_pk_mul_f32 v[108:109], v[90:91], s[14:15] op_sel_hi:[1,0]
	s_mov_b64 s[4:5], 0

; __device__ __forceinline__ unsigned pk2(float lo, float hi) { f32x2 v = {lo, hi}; bf16x2_t b = __builtin_convertvector(v, bf16x2_t); return __builtin_bit_cast(unsigned, b); }
; __device__ __forceinline__ float fsigmoid(float x) { return __builtin_amdgcn_rcpf(1.0f + __expf(-x)); }
;     __device__ __forceinline__ void operator()(const f32x4 (&acc)[2][2][4][2], const Unit& u, int wr, int wc, int fr, int fq) const {
;     ...
;             for (int m = 0; m < 4; ++m) { const int row = row0 + ai * HALF + m * 16; bf16_t* rowp = O + (size_t)row * ldc + col0;
;                 const float rs = 1.0f / sqrtf(ssq[row] * (1.0f / D) + RMS_EPS);
; #pragma unroll
;                 for (int bj = 0; bj < 2; ++bj) { f32x4 v0 = acc[ai][bj][m][0] * rs, v1 = acc[ai][bj][m][1] * rs;
;                     if (mode == 1) {
; #pragma unroll
;                         for (int j = 0; j < 4; ++j) { v0[j] = fsigmoid(v0[j]); v1[j] = fsigmoid(v1[j]); } }
;                     else if (mode == 2) { v0 = v0 * 0.08838834764831845f; v1 = v1 * 0.08838834764831845f; }
;                     u32x4 w; w.x = pk2(v0[0], v0[1]); w.y = pk2(v0[2], v0[3]); w.z = pk2(v1[0], v1[1]); w.w = pk2(v1[2], v1[3]);
;                     *(u32x4*)(rowp + bj * HALF) = w; } }
.LBB0_329:
	v_cvt_pk_bf16_f32 v82, v96, v97
	v_cvt_pk_bf16_f32 v83, v92, v93
	v_cvt_pk_bf16_f32 v84, v98, v99
	v_cvt_pk_bf16_f32 v85, v94, v95
	global_store_dwordx4 v[90:91], v[82:85], off offset:256
	s_cmp_gt_i32 s17, 1
	s_nop 0
	v_or_b32_e32 v82, 48, v146
	v_ashrrev_i32_e32 v83, 31, v82
	v_lshl_add_u64 v[84:85], v[82:83], 2, s[10:11]
	s_nop 0
	v_mov_b32_e32 v83, v170
	v_fmamk_f32 v83, v83, 0x39800000, v165
	v_mul_f32_e32 v84, 0x4f800000, v83
	v_cmp_gt_f32_e32 vcc, s83, v83
	s_nop 1
	v_cndmask_b32_e32 v83, v83, v84, vcc
	v_sqrt_f32_e32 v84, v83
	s_nop 0
	v_add_u32_e32 v85, -1, v84
	v_add_u32_e32 v86, 1, v84
	v_fma_f32 v87, -v85, v84, v83
	v_fma_f32 v88, -v86, v84, v83
	v_cmp_ge_f32_e64 s[4:5], 0, v87
	s_nop 1
	v_cndmask_b32_e64 v84, v84, v85, s[4:5]
	v_cmp_lt_f32_e64 s[4:5], 0, v88
	s_nop 1
	v_cndmask_b32_e64 v84, v84, v86, s[4:5]
	v_mul_f32_e32 v85, 0x37800000, v84
	v_cndmask_b32_e32 v84, v84, v85, vcc
	v_cmp_class_f32_e32 vcc, v83, v166
	s_nop 1
	v_cndmask_b32_e32 v83, v84, v83, vcc
	v_div_scale_f32 v84, s[4:5], v83, v83, 1.0
	v_rcp_f32_e32 v85, v84
	v_div_scale_f32 v86, vcc, 1.0, v83, 1.0
	s_mov_b64 s[4:5], -1
	v_fma_f32 v87, -v84, v85, 1.0
	v_fmac_f32_e32 v85, v87, v85
	v_mul_f32_e32 v87, v86, v85
	v_fma_f32 v88, -v84, v87, v86
	v_fmac_f32_e32 v87, v88, v85
	v_fma_f32 v84, -v84, v87, v86
	v_div_fmas_f32 v84, v84, v85, v87
	v_div_fixup_f32 v84, v84, v83, 1.0
	v_pk_mul_f32 v[80:81], v[80:81], v[84:85] op_sel_hi:[1,0]
	v_pk_mul_f32 v[78:79], v[78:79], v[84:85] op_sel_hi:[1,0]
	v_pk_mul_f32 v[76:77], v[76:77], v[84:85] op_sel_hi:[1,0]
	v_pk_mul_f32 v[74:75], v[74:75], v[84:85] op_sel_hi:[1,0]
	s_cbranch_scc0 .LBB0_331
	v_pk_mul_f32 v[86:87], v[80:81], s[14:15] op_sel_hi:[1,0]
	v_pk_mul_f32 v[90:91], v[78:79], s[14:15] op_sel_hi:[1,0]
	v_pk_mul_f32 v[88:89], v[76:77], s[14:15] op_sel_hi:[1,0]
	v_pk_mul_f32 v[92:93], v[74:75], s[14:15] op_sel_hi:[1,0]
	s_mov_b64 s[4:5], 0

; __device__ __forceinline__ unsigned pk2(float lo, float hi) { f32x2 v = {lo, hi}; bf16x2_t b = __builtin_convertvector(v, bf16x2_t); return __builtin_bit_cast(unsigned, b); }
; __device__ __forceinline__ float fsigmoid(float x) { return __builtin_amdgcn_rcpf(1.0f + __expf(-x)); }
;     __device__ __forceinline__ void operator()(const f32x4 (&acc)[2][2][4][2], const Unit& u, int wr, int wc, int fr, int fq) const {
;     ...
;             for (int m = 0; m < 4; ++m) { const int row = row0 + ai * HALF + m * 16; bf16_t* rowp = O + (size_t)row * ldc + col0;
;                 const float rs = 1.0f / sqrtf(ssq[row] * (1.0f / D) + RMS_EPS);
; #pragma unroll
;                 for (int bj = 0; bj < 2; ++bj) { f32x4 v0 = acc[ai][bj][m][0] * rs, v1 = acc[ai][bj][m][1] * rs;
;                     if (mode == 1) {
; #pragma unroll
;                         for (int j = 0; j < 4; ++j) { v0[j] = fsigmoid(v0[j]); v1[j] = fsigmoid(v1[j]); } }
;                     else if (mode == 2) { v0 = v0 * 0.08838834764831845f; v1 = v1 * 0.08838834764831845f; }
;                     u32x4 w; w.x = pk2(v0[0], v0[1]); w.y = pk2(v0[2], v0[3]); w.z = pk2(v1[0], v1[1]); w.w = pk2(v1[2], v1[3]);
;                     *(u32x4*)(rowp + bj * HALF) = w; } }
.LBB0_341:
	v_cvt_pk_bf16_f32 v66, v80, v81
	v_cvt_pk_bf16_f32 v67, v76, v77
	v_cvt_pk_bf16_f32 v68, v82, v83
	v_cvt_pk_bf16_f32 v69, v78, v79
	global_store_dwordx4 v[74:75], v[66:69], off offset:256
	s_nop 0
	s_cmp_gt_i32 s17, 1
	v_mov_b32_e32 v66, v171
	v_fmamk_f32 v66, v66, 0x39800000, v165
	v_mul_f32_e32 v67, 0x4f800000, v66
	v_cmp_gt_f32_e32 vcc, s83, v66
	s_nop 1
	v_cndmask_b32_e32 v66, v66, v67, vcc
	v_sqrt_f32_e32 v67, v66
	s_nop 0
	v_add_u32_e32 v68, -1, v67
	v_add_u32_e32 v69, 1, v67
	v_fma_f32 v70, -v68, v67, v66
	v_fma_f32 v71, -v69, v67, v66
	v_cmp_ge_f32_e64 s[4:5], 0, v70
	s_nop 1
	v_cndmask_b32_e64 v67, v67, v68, s[4:5]
	v_cmp_lt_f32_e64 s[4:5], 0, v71
	s_nop 1
	v_cndmask_b32_e64 v67, v67, v69, s[4:5]
	v_mul_f32_e32 v68, 0x37800000, v67
	v_cndmask_b32_e32 v67, v67, v68, vcc
	v_cmp_class_f32_e32 vcc, v66, v166
	s_nop 1
	v_cndmask_b32_e32 v66, v67, v66, vcc
	v_div_scale_f32 v67, s[4:5], v66, v66, 1.0
	v_rcp_f32_e32 v68, v67
	v_div_scale_f32 v69, vcc, 1.0, v66, 1.0
	s_mov_b64 s[4:5], -1
	v_fma_f32 v70, -v67, v68, 1.0
	v_fmac_f32_e32 v68, v70, v68
	v_mul_f32_e32 v70, v69, v68
	v_fma_f32 v71, -v67, v70, v69
	v_fmac_f32_e32 v70, v71, v68
	v_fma_f32 v67, -v67, v70, v69
	v_div_fmas_f32 v67, v67, v68, v70
	v_div_fixup_f32 v66, v67, v66, 1.0
	v_pk_mul_f32 v[64:65], v[64:65], v[66:67] op_sel_hi:[1,0]
	v_pk_mul_f32 v[62:63], v[62:63], v[66:67] op_sel_hi:[1,0]
	v_pk_mul_f32 v[60:61], v[60:61], v[66:67] op_sel_hi:[1,0]
	v_pk_mul_f32 v[58:59], v[58:59], v[66:67] op_sel_hi:[1,0]
	s_cbranch_scc0 .LBB0_343
	v_pk_mul_f32 v[68:69], v[64:65], s[14:15] op_sel_hi:[1,0]
	v_pk_mul_f32 v[72:73], v[62:63], s[14:15] op_sel_hi:[1,0]
	v_pk_mul_f32 v[70:71], v[60:61], s[14:15] op_sel_hi:[1,0]
	v_pk_mul_f32 v[74:75], v[58:59], s[14:15] op_sel_hi:[1,0]
	s_mov_b64 s[4:5], 0

; __device__ __forceinline__ unsigned pk2(float lo, float hi) { f32x2 v = {lo, hi}; bf16x2_t b = __builtin_convertvector(v, bf16x2_t); return __builtin_bit_cast(unsigned, b); }
; __device__ __forceinline__ float fsigmoid(float x) { return __builtin_amdgcn_rcpf(1.0f + __expf(-x)); }
;     __device__ __forceinline__ void operator()(const f32x4 (&acc)[2][2][4][2], const Unit& u, int wr, int wc, int fr, int fq) const {
;     ...
;             for (int m = 0; m < 4; ++m) { const int row = row0 + ai * HALF + m * 16; bf16_t* rowp = O + (size_t)row * ldc + col0;
;                 const float rs = 1.0f / sqrtf(ssq[row] * (1.0f / D) + RMS_EPS);
; #pragma unroll
;                 for (int bj = 0; bj < 2; ++bj) { f32x4 v0 = acc[ai][bj][m][0] * rs, v1 = acc[ai][bj][m][1] * rs;
;                     if (mode == 1) {
; #pragma unroll
;                         for (int j = 0; j < 4; ++j) { v0[j] = fsigmoid(v0[j]); v1[j] = fsigmoid(v1[j]); } }
;                     else if (mode == 2) { v0 = v0 * 0.08838834764831845f; v1 = v1 * 0.08838834764831845f; }
;                     u32x4 w; w.x = pk2(v0[0], v0[1]); w.y = pk2(v0[2], v0[3]); w.z = pk2(v1[0], v1[1]); w.w = pk2(v1[2], v1[3]);
;                     *(u32x4*)(rowp + bj * HALF) = w; } }
.LBB0_353:
	v_cvt_pk_bf16_f32 v50, v64, v65
	v_cvt_pk_bf16_f32 v51, v60, v61
	v_cvt_pk_bf16_f32 v52, v66, v67
	v_cvt_pk_bf16_f32 v53, v62, v63
	global_store_dwordx4 v[58:59], v[50:53], off offset:256
	s_nop 0
	s_cmp_gt_i32 s17, 1
	v_mov_b32_e32 v50, v172
	v_fmamk_f32 v50, v50, 0x39800000, v165
	v_mul_f32_e32 v51, 0x4f800000, v50
	v_cmp_gt_f32_e32 vcc, s83, v50
	s_nop 1
	v_cndmask_b32_e32 v50, v50, v51, vcc
	v_sqrt_f32_e32 v51, v50
	s_nop 0
	v_add_u32_e32 v52, -1, v51
	v_add_u32_e32 v53, 1, v51
	v_fma_f32 v54, -v52, v51, v50
	v_fma_f32 v55, -v53, v51, v50
	v_cmp_ge_f32_e64 s[4:5], 0, v54
	s_nop 1
	v_cndmask_b32_e64 v51, v51, v52, s[4:5]
	v_cmp_lt_f32_e64 s[4:5], 0, v55
	s_nop 1
	v_cndmask_b32_e64 v51, v51, v53, s[4:5]
	v_mul_f32_e32 v52, 0x37800000, v51
	v_cndmask_b32_e32 v51, v51, v52, vcc
	v_cmp_class_f32_e32 vcc, v50, v166
	s_nop 1
	v_cndmask_b32_e32 v50, v51, v50, vcc
	v_div_scale_f32 v51, s[4:5], v50, v50, 1.0
	v_rcp_f32_e32 v52, v51
	v_div_scale_f32 v53, vcc, 1.0, v50, 1.0
	s_mov_b64 s[4:5], -1
	v_fma_f32 v54, -v51, v52, 1.0
	v_fmac_f32_e32 v52, v54, v52
	v_mul_f32_e32 v54, v53, v52
	v_fma_f32 v55, -v51, v54, v53
	v_fmac_f32_e32 v54, v55, v52
	v_fma_f32 v51, -v51, v54, v53
	v_div_fmas_f32 v51, v51, v52, v54
	v_div_fixup_f32 v50, v51, v50, 1.0
	v_pk_mul_f32 v[48:49], v[48:49], v[50:51] op_sel_hi:[1,0]
	v_pk_mul_f32 v[46:47], v[46:47], v[50:51] op_sel_hi:[1,0]
	v_pk_mul_f32 v[44:45], v[44:45], v[50:51] op_sel_hi:[1,0]
	v_pk_mul_f32 v[42:43], v[42:43], v[50:51] op_sel_hi:[1,0]
	s_cbranch_scc0 .LBB0_355
	v_pk_mul_f32 v[52:53], v[48:49], s[14:15] op_sel_hi:[1,0]
	v_pk_mul_f32 v[56:57], v[46:47], s[14:15] op_sel_hi:[1,0]
	v_pk_mul_f32 v[54:55], v[44:45], s[14:15] op_sel_hi:[1,0]
	v_pk_mul_f32 v[58:59], v[42:43], s[14:15] op_sel_hi:[1,0]
	s_mov_b64 s[4:5], 0

; __device__ __forceinline__ unsigned pk2(float lo, float hi) { f32x2 v = {lo, hi}; bf16x2_t b = __builtin_convertvector(v, bf16x2_t); return __builtin_bit_cast(unsigned, b); }
; __device__ __forceinline__ float fsigmoid(float x) { return __builtin_amdgcn_rcpf(1.0f + __expf(-x)); }
;     __device__ __forceinline__ void operator()(const f32x4 (&acc)[2][2][4][2], const Unit& u, int wr, int wc, int fr, int fq) const {
;     ...
;             for (int m = 0; m < 4; ++m) { const int row = row0 + ai * HALF + m * 16; bf16_t* rowp = O + (size_t)row * ldc + col0;
;                 const float rs = 1.0f / sqrtf(ssq[row] * (1.0f / D) + RMS_EPS);
; #pragma unroll
;                 for (int bj = 0; bj < 2; ++bj) { f32x4 v0 = acc[ai][bj][m][0] * rs, v1 = acc[ai][bj][m][1] * rs;
;                     if (mode == 1) {
; #pragma unroll
;                         for (int j = 0; j < 4; ++j) { v0[j] = fsigmoid(v0[j]); v1[j] = fsigmoid(v1[j]); } }
;                     else if (mode == 2) { v0 = v0 * 0.08838834764831845f; v1 = v1 * 0.08838834764831845f; }
;                     u32x4 w; w.x = pk2(v0[0], v0[1]); w.y = pk2(v0[2], v0[3]); w.z = pk2(v1[0], v1[1]); w.w = pk2(v1[2], v1[3]);
;                     *(u32x4*)(rowp + bj * HALF) = w; } }
.LBB0_365:
	v_cvt_pk_bf16_f32 v34, v48, v49
	v_cvt_pk_bf16_f32 v35, v44, v45
	v_cvt_pk_bf16_f32 v36, v50, v51
	v_cvt_pk_bf16_f32 v37, v46, v47
	global_store_dwordx4 v[42:43], v[34:37], off offset:256
	s_nop 0
	s_cmp_gt_i32 s17, 1
	v_mov_b32_e32 v34, v173
	v_fmamk_f32 v34, v34, 0x39800000, v165
	v_mul_f32_e32 v35, 0x4f800000, v34
	v_cmp_gt_f32_e32 vcc, s83, v34
	s_nop 1
	v_cndmask_b32_e32 v34, v34, v35, vcc
	v_sqrt_f32_e32 v35, v34
	s_nop 0
	v_add_u32_e32 v36, -1, v35
	v_add_u32_e32 v37, 1, v35
	v_fma_f32 v38, -v36, v35, v34
	v_fma_f32 v39, -v37, v35, v34
	v_cmp_ge_f32_e64 s[4:5], 0, v38
	s_nop 1
	v_cndmask_b32_e64 v35, v35, v36, s[4:5]
	v_cmp_lt_f32_e64 s[4:5], 0, v39
	s_nop 1
	v_cndmask_b32_e64 v35, v35, v37, s[4:5]
	v_mul_f32_e32 v36, 0x37800000, v35
	v_cndmask_b32_e32 v35, v35, v36, vcc
	v_cmp_class_f32_e32 vcc, v34, v166
	s_nop 1
	v_cndmask_b32_e32 v34, v35, v34, vcc
	v_div_scale_f32 v35, s[4:5], v34, v34, 1.0
	v_rcp_f32_e32 v36, v35
	v_div_scale_f32 v37, vcc, 1.0, v34, 1.0
	s_mov_b64 s[4:5], -1
	v_fma_f32 v38, -v35, v36, 1.0
	v_fmac_f32_e32 v36, v38, v36
	v_mul_f32_e32 v38, v37, v36
	v_fma_f32 v39, -v35, v38, v37
	v_fmac_f32_e32 v38, v39, v36
	v_fma_f32 v35, -v35, v38, v37
	v_div_fmas_f32 v35, v35, v36, v38
	v_div_fixup_f32 v34, v35, v34, 1.0
	v_pk_mul_f32 v[32:33], v[32:33], v[34:35] op_sel_hi:[1,0]
	v_pk_mul_f32 v[30:31], v[30:31], v[34:35] op_sel_hi:[1,0]
	v_pk_mul_f32 v[28:29], v[28:29], v[34:35] op_sel_hi:[1,0]
	v_pk_mul_f32 v[26:27], v[26:27], v[34:35] op_sel_hi:[1,0]
	s_cbranch_scc0 .LBB0_367
	v_pk_mul_f32 v[36:37], v[32:33], s[14:15] op_sel_hi:[1,0]
	v_pk_mul_f32 v[40:41], v[30:31], s[14:15] op_sel_hi:[1,0]
	v_pk_mul_f32 v[38:39], v[28:29], s[14:15] op_sel_hi:[1,0]
	v_pk_mul_f32 v[42:43], v[26:27], s[14:15] op_sel_hi:[1,0]
	s_mov_b64 s[4:5], 0

; __device__ __forceinline__ unsigned pk2(float lo, float hi) { f32x2 v = {lo, hi}; bf16x2_t b = __builtin_convertvector(v, bf16x2_t); return __builtin_bit_cast(unsigned, b); }
; __device__ __forceinline__ float fsigmoid(float x) { return __builtin_amdgcn_rcpf(1.0f + __expf(-x)); }
;     __device__ __forceinline__ void operator()(const f32x4 (&acc)[2][2][4][2], const Unit& u, int wr, int wc, int fr, int fq) const {
;     ...
;             for (int m = 0; m < 4; ++m) { const int row = row0 + ai * HALF + m * 16; bf16_t* rowp = O + (size_t)row * ldc + col0;
;                 const float rs = 1.0f / sqrtf(ssq[row] * (1.0f / D) + RMS_EPS);
; #pragma unroll
;                 for (int bj = 0; bj < 2; ++bj) { f32x4 v0 = acc[ai][bj][m][0] * rs, v1 = acc[ai][bj][m][1] * rs;
;                     if (mode == 1) {
; #pragma unroll
;                         for (int j = 0; j < 4; ++j) { v0[j] = fsigmoid(v0[j]); v1[j] = fsigmoid(v1[j]); } }
;                     else if (mode == 2) { v0 = v0 * 0.08838834764831845f; v1 = v1 * 0.08838834764831845f; }
;                     u32x4 w; w.x = pk2(v0[0], v0[1]); w.y = pk2(v0[2], v0[3]); w.z = pk2(v1[0], v1[1]); w.w = pk2(v1[2], v1[3]);
;                     *(u32x4*)(rowp + bj * HALF) = w; } }
.LBB0_377:
	v_cvt_pk_bf16_f32 v18, v32, v33
	v_cvt_pk_bf16_f32 v19, v28, v29
	v_cvt_pk_bf16_f32 v20, v34, v35
	v_cvt_pk_bf16_f32 v21, v30, v31
	global_store_dwordx4 v[26:27], v[18:21], off offset:256
	s_nop 0
	s_cmp_gt_i32 s17, 1
	v_mov_b32_e32 v18, v174
	v_fmamk_f32 v18, v18, 0x39800000, v165
	v_mul_f32_e32 v19, 0x4f800000, v18
	v_cmp_gt_f32_e32 vcc, s83, v18
	s_nop 1
	v_cndmask_b32_e32 v18, v18, v19, vcc
	v_sqrt_f32_e32 v19, v18
	s_nop 0
	v_add_u32_e32 v20, -1, v19
	v_add_u32_e32 v21, 1, v19
	v_fma_f32 v22, -v20, v19, v18
	v_fma_f32 v23, -v21, v19, v18
	v_cmp_ge_f32_e64 s[4:5], 0, v22
	s_nop 1
	v_cndmask_b32_e64 v19, v19, v20, s[4:5]
	v_cmp_lt_f32_e64 s[4:5], 0, v23
	s_nop 1
	v_cndmask_b32_e64 v19, v19, v21, s[4:5]
	v_mul_f32_e32 v20, 0x37800000, v19
	v_cndmask_b32_e32 v19, v19, v20, vcc
	v_cmp_class_f32_e32 vcc, v18, v166
	s_nop 1
	v_cndmask_b32_e32 v18, v19, v18, vcc
	v_div_scale_f32 v19, s[4:5], v18, v18, 1.0
	v_rcp_f32_e32 v20, v19
	v_div_scale_f32 v21, vcc, 1.0, v18, 1.0
	s_mov_b64 s[4:5], -1
	v_fma_f32 v22, -v19, v20, 1.0
	v_fmac_f32_e32 v20, v22, v20
	v_mul_f32_e32 v22, v21, v20
	v_fma_f32 v23, -v19, v22, v21
	v_fmac_f32_e32 v22, v23, v20
	v_fma_f32 v19, -v19, v22, v21
	v_div_fmas_f32 v19, v19, v20, v22
	v_div_fixup_f32 v18, v19, v18, 1.0
	v_pk_mul_f32 v[16:17], v[16:17], v[18:19] op_sel_hi:[1,0]
	v_pk_mul_f32 v[14:15], v[14:15], v[18:19] op_sel_hi:[1,0]
	v_pk_mul_f32 v[12:13], v[12:13], v[18:19] op_sel_hi:[1,0]
	v_pk_mul_f32 v[10:11], v[10:11], v[18:19] op_sel_hi:[1,0]
	s_cbranch_scc0 .LBB0_379
	v_pk_mul_f32 v[20:21], v[16:17], s[14:15] op_sel_hi:[1,0]
	v_pk_mul_f32 v[24:25], v[14:15], s[14:15] op_sel_hi:[1,0]
	v_pk_mul_f32 v[22:23], v[12:13], s[14:15] op_sel_hi:[1,0]
	v_pk_mul_f32 v[26:27], v[10:11], s[14:15] op_sel_hi:[1,0]
	s_mov_b64 s[4:5], 0

; #define LAS __attribute__((address_space(3)))
; #define MFMA32(a, b, c) __builtin_amdgcn_mfma_f32_32x32x16_bf16((a), (b), (c), 0, 0, 0)
; __device__ __forceinline__ void mlstm_passC(LAS unsigned char* lds, const bf16* P, const float* GT, const float* b_i, const float* b_f, const bf16* QC, const bf16* KC, ...
;     ...
;     for (int i = 0; i < 2; ++i) { const int id = tid + 512 * i, s = id >> 4, cc = (id & 15) * 8; const size_t go = (size_t)(t0 + s) * 1024 + h * DK + cc;
;         *(LAS u32x4*)(QS + s * KS_STRIDE + cc * 2) = *(const u32x4*)(QC + go); *(LAS u32x4*)(KS + s * KS_STRIDE + cc * 2) = *(const u32x4*)(KC + go); }
; #pragma unroll
;     for (int i = 0; i < 4; ++i) { const int id = tid + 512 * i, s = id >> 5, cc = (id & 31) * 8;
;         *(LAS u32x4*)(VS + s * VS_STRIDE + cc * 2) = *(const u32x4*)(P + (size_t)(t0 + s) * NP + PC_MV + h * DV + cc); }
;     const int tb = wave & 1, dvq = wave >> 1, tl = 32 * tb + (lane & 31), hh = lane >> 5, q4 = (lane & 15) >> 2, p4 = lane & 3, g2 = (lane >> 4) & 1;
;     bf16x8 cfr[2][8];
;     {   const bf16* cst = CST + (size_t)unit * (DV * DK);
; #pragma unroll
;         for (int db = 0; db < 2; ++db)
; #pragma unroll
;             for (int ks = 0; ks < 8; ++ks) cfr[db][ks] = *(const bf16x8*)(cst + (size_t)(64 * dvq + 32 * db + (lane & 31)) * DK + 16 * ks + 8 * hh); }
;     __builtin_amdgcn_sched_barrier(0);
;     __syncthreads();
;     bf16x8 qf[8];
; #pragma unroll
;     for (int ks = 0; ks < 8; ++ks) qf[ks] = *(LAS const bf16x8*)(QS + tl * KS_STRIDE + (16 * ks + 8 * hh) * 2);
;     const float cmt = CM[tl], dect = DEC[tl];
;     bf16x8 wf[2][2]; float dsum = 0.f;
; #pragma unroll
;     for (int sb = 0; sb < 2; ++sb) {
;         if (sb <= tb) {
;             f32x16 st;
; #pragma unroll
;             for (int r = 0; r < 16; ++r) st[r] = 0.f;
; #pragma unroll
;             for (int ks = 0; ks < 8; ++ks) { const bf16x8 kf = *(LAS const bf16x8*)(KS + (32 * sb + (lane & 31)) * KS_STRIDE + (16 * ks + 8 * hh) * 2); st = MFMA32(kf, qf[ks], st); }
.LBB0_604:
	s_and_b32 s15, s74, 0xffffff80
	s_ashr_i32 s26, s15, 31
	v_or_b32_e32 v2, s3, v170
	v_mov_b32_e32 v7, s26
	v_or_b32_e32 v6, s15, v122
	v_lshlrev_b32_e32 v124, 10, v2
	v_lshl_add_u64 v[2:3], v[6:7], 0, v[124:125]
	v_lshlrev_b64 v[8:9], 1, v[2:3]
	v_lshl_add_u64 v[2:3], s[46:47], 0, v[8:9]
	global_load_dwordx4 v[18:21], v[2:3], off
	v_add_lshl_u32 v124, s3, v171, 10
	s_lshl_b32 s76, s14, 8
	s_ashr_i32 s77, s76, 31
	s_lshl_b64 s[14:15], s[76:77], 1
	v_mov_b32_e32 v163, v125
	s_lshr_b32 s26, s33, 7
	s_lshl_b32 s86, s26, 6
	v_lshl_add_u64 v[2:3], s[48:49], 0, v[8:9]
	global_load_dwordx4 v[34:37], v[2:3], off
	v_lshl_add_u64 v[2:3], v[6:7], 0, v[124:125]
	v_lshlrev_b64 v[6:7], 1, v[2:3]
	v_lshl_add_u64 v[2:3], s[46:47], 0, v[6:7]
	global_load_dwordx4 v[38:41], v[2:3], off
	v_lshl_add_u64 v[2:3], s[48:49], 0, v[6:7]
	global_load_dwordx4 v[42:45], v[2:3], off
	v_or_b32_e32 v2, s3, v172
	v_mul_u32_u24_e32 v2, 0x5000, v2
	v_lshlrev_b32_e32 v124, 1, v2
	v_lshl_add_u64 v[2:3], s[24:25], 0, v[124:125]
	v_lshl_add_u64 v[2:3], v[2:3], 0, s[14:15]
	v_lshl_add_u64 v[2:3], v[2:3], 0, v[162:163]
	v_add_co_u32_e32 v2, vcc, s83, v2
	s_nop 1
	v_addc_co_u32_e32 v3, vcc, 0, v3, vcc
	global_load_dwordx4 v[46:49], v[2:3], off
	v_or_b32_e32 v2, s3, v173
	v_mul_u32_u24_e32 v2, 0x5000, v2
	v_lshlrev_b32_e32 v124, 1, v2
	v_lshl_add_u64 v[2:3], s[24:25], 0, v[124:125]
	v_lshl_add_u64 v[2:3], v[2:3], 0, s[14:15]
	v_lshl_add_u64 v[2:3], v[2:3], 0, v[162:163]
	v_add_co_u32_e32 v2, vcc, s83, v2
	s_nop 1
	v_addc_co_u32_e32 v3, vcc, 0, v3, vcc
	global_load_dwordx4 v[50:53], v[2:3], off
	v_or_b32_e32 v2, s3, v174
	v_mul_u32_u24_e32 v2, 0x5000, v2
	v_lshlrev_b32_e32 v124, 1, v2
	v_lshl_add_u64 v[2:3], s[24:25], 0, v[124:125]
	v_lshl_add_u64 v[2:3], v[2:3], 0, s[14:15]
	v_lshl_add_u64 v[2:3], v[2:3], 0, v[162:163]
	v_add_co_u32_e32 v2, vcc, s83, v2
	s_nop 1
	v_addc_co_u32_e32 v3, vcc, 0, v3, vcc
	global_load_dwordx4 v[54:57], v[2:3], off
	v_add_u32_e32 v2, s3, v175
	v_mul_u32_u24_e32 v2, 0x5000, v2
	v_lshlrev_b32_e32 v124, 1, v2
	v_lshl_add_u64 v[2:3], s[24:25], 0, v[124:125]
	v_lshl_add_u64 v[2:3], v[2:3], 0, s[14:15]
	v_lshl_add_u64 v[2:3], v[2:3], 0, v[162:163]
	v_add_co_u32_e32 v2, vcc, s83, v2
	s_lshl_b64 s[14:15], s[78:79], 16
	s_nop 0
	v_addc_co_u32_e32 v3, vcc, 0, v3, vcc
	global_load_dwordx4 v[58:61], v[2:3], off
	s_waitcnt vmcnt(0)
	ds_write_b128 v226, v[18:21]
	ds_write_b128 v226, v[34:37] offset:17408
	ds_write_b128 v227, v[38:41]
	ds_write_b128 v227, v[42:45] offset:17408
	ds_write_b128 v228, v[46:49] offset:34816
	ds_write_b128 v229, v[50:53] offset:34816
	ds_write_b128 v228, v[54:57] offset:51712
	ds_write_b128 v230, v[58:61] offset:34816
	v_or_b32_e32 v124, s86, v176
	v_lshl_add_u64 v[2:3], v[128:129], 0, s[14:15]
	v_lshlrev_b64 v[4:5], 8, v[124:125]
	v_lshl_add_u64 v[4:5], v[2:3], 0, v[4:5]
	v_or_b32_e32 v124, 32, v124
	global_load_dwordx4 v[110:113], v[4:5], off
	global_load_dwordx4 v[106:109], v[4:5], off offset:32
	global_load_dwordx4 v[102:105], v[4:5], off offset:64
	global_load_dwordx4 v[98:101], v[4:5], off offset:96
	global_load_dwordx4 v[94:97], v[4:5], off offset:128
	global_load_dwordx4 v[90:93], v[4:5], off offset:160
	global_load_dwordx4 v[30:33], v[4:5], off offset:192
	global_load_dwordx4 v[26:29], v[4:5], off offset:224
	v_lshlrev_b64 v[4:5], 8, v[124:125]
	v_lshl_add_u64 v[2:3], v[2:3], 0, v[4:5]
	global_load_dwordx4 v[18:21], v[2:3], off
	global_load_dwordx4 v[58:61], v[2:3], off offset:32
	global_load_dwordx4 v[54:57], v[2:3], off offset:64
	global_load_dwordx4 v[50:53], v[2:3], off offset:96
	global_load_dwordx4 v[46:49], v[2:3], off offset:128
	global_load_dwordx4 v[42:45], v[2:3], off offset:160
	global_load_dwordx4 v[38:41], v[2:3], off offset:192
	global_load_dwordx4 v[34:37], v[2:3], off offset:224
	s_bfe_u32 s14, s33, 0x10006
	v_lshl_or_b32 v124, s14, 5, v176
	s_movk_i32 s15, 0x110
	v_mad_u32_u24 v167, v124, s15, 0
	v_add_u32_e32 v2, v167, v126
	v_lshl_add_u32 v163, v124, 2, 0
	s_waitcnt lgkmcnt(0)
	s_barrier
	ds_read_b128 v[22:25], v2
	ds_read_b128 v[86:89], v2 offset:32
	ds_read_b128 v[82:85], v2 offset:64
	ds_read_b128 v[78:81], v2 offset:96
	ds_read_b128 v[74:77], v2 offset:128
	ds_read_b128 v[70:73], v2 offset:160
	ds_read_b128 v[66:69], v2 offset:192
	ds_read_b128 v[62:65], v2 offset:224
	v_add_u32_e32 v2, 0x10d00, v163
	ds_read_b32 v114, v2
	v_add_u32_e32 v2, 0x10e00, v163
	ds_read_b32 v164, v2
	ds_read_b128 v[2:5], v235 offset:17408
	ds_read_b128 v[116:119], v235 offset:17440
	s_waitcnt lgkmcnt(1)
	v_mfma_f32_32x32x16_bf16 v[2:17], v[2:5], v[22:25], 0
	v_cmp_le_u32_e32 vcc, v177, v124
	s_bitcmp1_b32 s33, 6
	s_cselect_b64 s[78:79], -1, 0
	s_cmp_eq_u32 s14, 0
	s_waitcnt lgkmcnt(0)
	v_mfma_f32_32x32x16_bf16 v[2:17], v[116:119], v[86:89], v[2:17]
	ds_read_b128 v[116:119], v235 offset:17472
	s_waitcnt lgkmcnt(0)
	v_mfma_f32_32x32x16_bf16 v[2:17], v[116:119], v[82:85], v[2:17]
	ds_read_b128 v[116:119], v235 offset:17504
	s_waitcnt lgkmcnt(0)
	v_mfma_f32_32x32x16_bf16 v[2:17], v[116:119], v[78:81], v[2:17]
	ds_read_b128 v[116:119], v235 offset:17536
	s_waitcnt lgkmcnt(0)
	v_mfma_f32_32x32x16_bf16 v[2:17], v[116:119], v[74:77], v[2:17]
	ds_read_b128 v[116:119], v235 offset:17568
	s_waitcnt lgkmcnt(0)
	v_mfma_f32_32x32x16_bf16 v[2:17], v[116:119], v[70:73], v[2:17]
	ds_read_b128 v[116:119], v235 offset:17600
	s_waitcnt lgkmcnt(0)
	v_mfma_f32_32x32x16_bf16 v[2:17], v[116:119], v[66:69], v[2:17]
	ds_read_b128 v[116:119], v235 offset:17632
	s_waitcnt lgkmcnt(0)
	v_mfma_f32_32x32x16_bf16 v[2:17], v[116:119], v[62:65], v[2:17]
	ds_read_b64 v[116:117], v180
	s_waitcnt lgkmcnt(0)
; __device__ __forceinline__ int crow(int r, int hi) { return (r & 3) + 8 * (r >> 2) + 4 * hi; }
; __device__ __forceinline__ void mlstm_passC(LAS unsigned char* lds, const bf16* P, const float* GT, const float* b_i, const float* b_f, const bf16* QC, const bf16* KC, ...
;     ...
;             float w[16];
; #pragma unroll
;             for (int r = 0; r < 16; ++r) { const int s = 32 * sb + crow(r, hh); const float e = __expf(GV[s] - cmt); w[r] = (s <= tl) ? st[r] * e : 0.f; dsum += w[r]; }
;             wf[sb][0] = pack8(w[0], w[1], w[2], w[3], w[4], w[5], w[6], w[7]);
;             wf[sb][1] = pack8(w[8], w[9], w[10], w[11], w[12], w[13], w[14], w[15]);
	v_sub_f32_e32 v115, v116, v114
	v_mul_f32_e32 v115, 0x3fb8aa3b, v115
	v_exp_f32_e32 v115, v115
	s_nop 6
	v_mul_f32_e32 v2, v2, v115
	v_sub_f32_e32 v115, v117, v114
	v_mul_f32_e32 v115, 0x3fb8aa3b, v115
	v_exp_f32_e32 v115, v115
	v_cndmask_b32_e32 v165, 0, v2, vcc
	v_cmp_lt_u32_e32 vcc, v177, v124
	v_add_f32_e32 v2, 0, v165
	v_mul_f32_e32 v3, v3, v115
	v_cndmask_b32_e32 v236, 0, v3, vcc
	v_add_f32_e32 v115, v2, v236
	ds_read_b32 v2, v181
	ds_read_b32 v3, v182
	v_cmp_le_u32_e32 vcc, v1, v124
	s_waitcnt lgkmcnt(1)
	v_sub_f32_e32 v2, v2, v114
	s_waitcnt lgkmcnt(0)
	v_sub_f32_e32 v3, v3, v114
	v_mul_f32_e32 v2, 0x3fb8aa3b, v2
	v_mul_f32_e32 v3, 0x3fb8aa3b, v3
	v_exp_f32_e32 v2, v2
	v_exp_f32_e32 v3, v3
	s_nop 0
	v_pk_mul_f32 v[2:3], v[4:5], v[2:3]
	s_nop 0
	v_cndmask_b32_e32 v237, 0, v3, vcc
	v_cmp_le_u32_e32 vcc, v130, v124
	ds_read_b32 v3, v184
	s_waitcnt lgkmcnt(0)
	v_sub_f32_e32 v3, v3, v114
	v_cndmask_b32_e32 v238, 0, v2, vcc
	v_add_f32_e32 v2, v115, v238
	v_add_f32_e32 v4, v2, v237
	ds_read_b32 v2, v183
	v_mul_f32_e32 v3, 0x3fb8aa3b, v3
	v_exp_f32_e32 v3, v3
	v_cmp_le_u32_e32 vcc, v123, v124
	s_waitcnt lgkmcnt(0)
	v_sub_f32_e32 v2, v2, v114
	v_mul_f32_e32 v2, 0x3fb8aa3b, v2
	v_exp_f32_e32 v2, v2
	s_nop 0
	v_pk_mul_f32 v[2:3], v[6:7], v[2:3]
	s_nop 0
	v_cndmask_b32_e32 v239, 0, v3, vcc
	v_cmp_le_u32_e32 vcc, v132, v124
	ds_read_b32 v3, v186
	s_waitcnt lgkmcnt(0)
	v_sub_f32_e32 v3, v3, v114
	v_cndmask_b32_e32 v240, 0, v2, vcc
	v_add_f32_e32 v2, v4, v240
	v_add_f32_e32 v4, v2, v239
	ds_read_b32 v2, v185
	v_mul_f32_e32 v3, 0x3fb8aa3b, v3
	v_exp_f32_e32 v3, v3
	v_cmp_le_u32_e32 vcc, v127, v124
	s_waitcnt lgkmcnt(0)
	v_sub_f32_e32 v2, v2, v114
	v_mul_f32_e32 v2, 0x3fb8aa3b, v2
	v_exp_f32_e32 v2, v2
	s_nop 0
	v_pk_mul_f32 v[2:3], v[8:9], v[2:3]
	s_nop 0
	v_cndmask_b32_e32 v241, 0, v3, vcc
	v_cmp_le_u32_e32 vcc, v134, v124
	ds_read_b32 v3, v188
	s_waitcnt lgkmcnt(0)
	v_sub_f32_e32 v3, v3, v114
	v_cndmask_b32_e32 v242, 0, v2, vcc
	v_add_f32_e32 v2, v4, v242
	v_add_f32_e32 v4, v2, v241
	ds_read_b32 v2, v187
	v_mul_f32_e32 v3, 0x3fb8aa3b, v3
	v_exp_f32_e32 v3, v3
	v_cmp_le_u32_e32 vcc, v131, v124
	s_waitcnt lgkmcnt(0)
	v_sub_f32_e32 v2, v2, v114
	v_mul_f32_e32 v2, 0x3fb8aa3b, v2
	v_exp_f32_e32 v2, v2
	s_nop 0
	v_pk_mul_f32 v[2:3], v[10:11], v[2:3]
	s_nop 0
	v_cndmask_b32_e32 v243, 0, v3, vcc
	v_cmp_le_u32_e32 vcc, v136, v124
	ds_read_b32 v3, v190
	s_waitcnt lgkmcnt(0)
	v_sub_f32_e32 v3, v3, v114
	v_cndmask_b32_e32 v244, 0, v2, vcc
	v_add_f32_e32 v2, v4, v244
	v_add_f32_e32 v4, v2, v243
	ds_read_b32 v2, v189
	v_mul_f32_e32 v3, 0x3fb8aa3b, v3
	v_exp_f32_e32 v3, v3
	v_cmp_le_u32_e32 vcc, v133, v124
	s_waitcnt lgkmcnt(0)
	v_sub_f32_e32 v2, v2, v114
	v_mul_f32_e32 v2, 0x3fb8aa3b, v2
	v_exp_f32_e32 v2, v2
	s_nop 0
	v_pk_mul_f32 v[2:3], v[12:13], v[2:3]
	s_nop 0
	v_cndmask_b32_e32 v245, 0, v3, vcc
	v_cmp_le_u32_e32 vcc, v138, v124
	ds_read_b32 v3, v197
	s_waitcnt lgkmcnt(0)
	v_sub_f32_e32 v3, v3, v114
	v_cndmask_b32_e32 v246, 0, v2, vcc
	v_add_f32_e32 v2, v4, v246
	v_add_f32_e32 v4, v2, v245
	ds_read_b32 v2, v191
	v_mul_f32_e32 v3, 0x3fb8aa3b, v3
	v_exp_f32_e32 v3, v3
	v_cmp_le_u32_e32 vcc, v135, v124
	s_waitcnt lgkmcnt(0)
	v_sub_f32_e32 v2, v2, v114
	v_mul_f32_e32 v2, 0x3fb8aa3b, v2
	v_exp_f32_e32 v2, v2
	s_nop 0
	v_pk_mul_f32 v[2:3], v[14:15], v[2:3]
	s_nop 0
	v_cndmask_b32_e32 v247, 0, v3, vcc
	v_cmp_le_u32_e32 vcc, v140, v124
	ds_read_b32 v3, v199
	s_waitcnt lgkmcnt(0)
	v_sub_f32_e32 v3, v3, v114
	v_cndmask_b32_e32 v248, 0, v2, vcc
	v_add_f32_e32 v2, v4, v248
	v_add_f32_e32 v4, v2, v247
	ds_read_b32 v2, v198
	v_mul_f32_e32 v3, 0x3fb8aa3b, v3
	v_exp_f32_e32 v3, v3
	v_cmp_le_u32_e32 vcc, v137, v124
	s_waitcnt lgkmcnt(0)
	v_sub_f32_e32 v2, v2, v114
	v_mul_f32_e32 v2, 0x3fb8aa3b, v2
	v_exp_f32_e32 v2, v2
	s_nop 0
	v_pk_mul_f32 v[2:3], v[16:17], v[2:3]
	s_nop 0
	v_cndmask_b32_e32 v249, 0, v3, vcc
	v_cmp_le_u32_e32 vcc, v142, v124
	s_nop 1
	v_cndmask_b32_e32 v250, 0, v2, vcc
	v_add_f32_e32 v2, v4, v250
	v_add_f32_e32 v166, v2, v249
	s_cbranch_scc1 .LBB0_606
; #define LAS __attribute__((address_space(3)))
; __device__ __forceinline__ int crow(int r, int hi) { return (r & 3) + 8 * (r >> 2) + 4 * hi; }
; #define MFMA32(a, b, c) __builtin_amdgcn_mfma_f32_32x32x16_bf16((a), (b), (c), 0, 0, 0)
; __device__ __forceinline__ void mlstm_passC(LAS unsigned char* lds, const bf16* P, const float* GT, const float* b_i, const float* b_f, const bf16* QC, const bf16* KC, ...
;     ...
;     for (int sb = 0; sb < 2; ++sb) {
;         if (sb <= tb) {
;             f32x16 st;
; #pragma unroll
;             for (int r = 0; r < 16; ++r) st[r] = 0.f;
; #pragma unroll
;             for (int ks = 0; ks < 8; ++ks) { const bf16x8 kf = *(LAS const bf16x8*)(KS + (32 * sb + (lane & 31)) * KS_STRIDE + (16 * ks + 8 * hh) * 2); st = MFMA32(kf, qf[ks], st); }
;             float w[16];
; #pragma unroll
;             for (int r = 0; r < 16; ++r) { const int s = 32 * sb + crow(r, hh); const float e = __expf(GV[s] - cmt); w[r] = (s <= tl) ? st[r] * e : 0.f; dsum += w[r]; }
;             wf[sb][0] = pack8(w[0], w[1], w[2], w[3], w[4], w[5], w[6], w[7]);
;             wf[sb][1] = pack8(w[8], w[9], w[10], w[11], w[12], w[13], w[14], w[15]);
;         } else { wf[sb][0] = (bf16x8){0, 0, 0, 0, 0, 0, 0, 0}; wf[sb][1] = wf[sb][0]; }
	ds_read_b128 v[2:5], v235 offset:26112
	ds_read_b128 v[116:119], v235 offset:26144
	v_cmp_le_u32_e32 vcc, v139, v124
	s_waitcnt lgkmcnt(1)
	v_mfma_f32_32x32x16_bf16 v[2:17], v[2:5], v[22:25], 0
	ds_read_b32 v115, v200
	s_waitcnt lgkmcnt(0)
	v_sub_f32_e32 v115, v115, v114
	v_mul_f32_e32 v115, 0x3fb8aa3b, v115
	v_mfma_f32_32x32x16_bf16 v[2:17], v[116:119], v[86:89], v[2:17]
	ds_read_b128 v[116:119], v235 offset:26176
	s_waitcnt lgkmcnt(0)
	v_mfma_f32_32x32x16_bf16 v[2:17], v[116:119], v[82:85], v[2:17]
	ds_read_b128 v[116:119], v235 offset:26208
	s_waitcnt lgkmcnt(0)
	v_mfma_f32_32x32x16_bf16 v[2:17], v[116:119], v[78:81], v[2:17]
	ds_read_b128 v[116:119], v235 offset:26240
	s_waitcnt lgkmcnt(0)
	v_mfma_f32_32x32x16_bf16 v[2:17], v[116:119], v[74:77], v[2:17]
	ds_read_b128 v[116:119], v235 offset:26272
	s_waitcnt lgkmcnt(0)
	v_mfma_f32_32x32x16_bf16 v[2:17], v[116:119], v[70:73], v[2:17]
	ds_read_b128 v[116:119], v235 offset:26304
	s_waitcnt lgkmcnt(0)
	v_mfma_f32_32x32x16_bf16 v[2:17], v[116:119], v[66:69], v[2:17]
	ds_read_b128 v[116:119], v235 offset:26336
	s_waitcnt lgkmcnt(0)
	v_mfma_f32_32x32x16_bf16 v[2:17], v[116:119], v[62:65], v[2:17]
	v_exp_f32_e32 v116, v115
	ds_read_b32 v115, v201
	s_waitcnt lgkmcnt(0)
	v_sub_f32_e32 v115, v115, v114
	v_mul_f32_e32 v115, 0x3fb8aa3b, v115
	v_exp_f32_e32 v117, v115
	s_nop 5
	v_pk_mul_f32 v[2:3], v[2:3], v[116:117]
	s_nop 0
	v_cndmask_b32_e32 v115, 0, v3, vcc
	v_cmp_le_u32_e32 vcc, v144, v124
	ds_read_b32 v3, v203
	s_waitcnt lgkmcnt(0)
	v_sub_f32_e32 v3, v3, v114
	v_cndmask_b32_e32 v116, 0, v2, vcc
	v_add_f32_e32 v2, v166, v116
	v_add_f32_e32 v117, v2, v115
	ds_read_b32 v2, v202
	v_mul_f32_e32 v3, 0x3fb8aa3b, v3
	v_exp_f32_e32 v3, v3
	v_cmp_le_u32_e32 vcc, v141, v124
	s_waitcnt lgkmcnt(0)
	v_sub_f32_e32 v2, v2, v114
	v_mul_f32_e32 v2, 0x3fb8aa3b, v2
	v_exp_f32_e32 v2, v2
	s_nop 0
	v_pk_mul_f32 v[2:3], v[4:5], v[2:3]
	s_nop 0
	v_cndmask_b32_e32 v4, 0, v3, vcc
	v_cmp_le_u32_e32 vcc, v146, v124
	ds_read_b32 v3, v205
	s_waitcnt lgkmcnt(0)
	v_sub_f32_e32 v3, v3, v114
	v_cndmask_b32_e32 v5, 0, v2, vcc
	v_add_f32_e32 v2, v117, v5
	v_add_f32_e32 v117, v2, v4
	ds_read_b32 v2, v204
	v_mul_f32_e32 v3, 0x3fb8aa3b, v3
	v_exp_f32_e32 v3, v3
	v_cmp_le_u32_e32 vcc, v143, v124
	s_waitcnt lgkmcnt(0)
	v_sub_f32_e32 v2, v2, v114
	v_mul_f32_e32 v2, 0x3fb8aa3b, v2
	v_exp_f32_e32 v2, v2
	s_nop 0
	v_pk_mul_f32 v[2:3], v[6:7], v[2:3]
	s_nop 0
	v_cndmask_b32_e32 v6, 0, v3, vcc
	v_cmp_le_u32_e32 vcc, v148, v124
	ds_read_b32 v3, v207
	s_waitcnt lgkmcnt(0)
	v_sub_f32_e32 v3, v3, v114
	v_cndmask_b32_e32 v7, 0, v2, vcc
	v_add_f32_e32 v2, v117, v7
	v_add_f32_e32 v117, v2, v6
	ds_read_b32 v2, v206
	v_mul_f32_e32 v3, 0x3fb8aa3b, v3
	v_exp_f32_e32 v3, v3
	v_cmp_le_u32_e32 vcc, v145, v124
	s_waitcnt lgkmcnt(0)
	v_sub_f32_e32 v2, v2, v114
	v_mul_f32_e32 v2, 0x3fb8aa3b, v2
	v_exp_f32_e32 v2, v2
	s_nop 0
	v_pk_mul_f32 v[2:3], v[8:9], v[2:3]
	s_nop 0
	v_cndmask_b32_e32 v8, 0, v3, vcc
	v_cmp_le_u32_e32 vcc, v150, v124
	ds_read_b32 v3, v209
	s_waitcnt lgkmcnt(0)
	v_sub_f32_e32 v3, v3, v114
	v_cndmask_b32_e32 v9, 0, v2, vcc
	v_add_f32_e32 v2, v117, v9
	v_add_f32_e32 v117, v2, v8
	ds_read_b32 v2, v208
	v_mul_f32_e32 v3, 0x3fb8aa3b, v3
	v_exp_f32_e32 v3, v3
	v_cmp_le_u32_e32 vcc, v147, v124
	s_waitcnt lgkmcnt(0)
	v_sub_f32_e32 v2, v2, v114
	v_mul_f32_e32 v2, 0x3fb8aa3b, v2
	v_exp_f32_e32 v2, v2
	s_nop 0
	v_pk_mul_f32 v[2:3], v[10:11], v[2:3]
	s_nop 0
	v_cndmask_b32_e32 v10, 0, v3, vcc
	v_cmp_le_u32_e32 vcc, v152, v124
	ds_read_b32 v3, v211
	s_waitcnt lgkmcnt(0)
	v_sub_f32_e32 v3, v3, v114
	v_cndmask_b32_e32 v11, 0, v2, vcc
	v_add_f32_e32 v2, v117, v11
	v_add_f32_e32 v117, v2, v10
	ds_read_b32 v2, v210
	v_mul_f32_e32 v3, 0x3fb8aa3b, v3
	v_exp_f32_e32 v3, v3
	v_cmp_le_u32_e32 vcc, v149, v124
	v_cvt_pk_bf16_f32 v118, v11, v10
	s_waitcnt lgkmcnt(0)
	v_sub_f32_e32 v2, v2, v114
	v_mul_f32_e32 v2, 0x3fb8aa3b, v2
	v_exp_f32_e32 v2, v2
	s_nop 0
	v_pk_mul_f32 v[2:3], v[12:13], v[2:3]
	s_nop 0
	v_cndmask_b32_e32 v12, 0, v3, vcc
	v_cmp_le_u32_e32 vcc, v154, v124
	ds_read_b32 v3, v213
	s_waitcnt lgkmcnt(0)
	v_sub_f32_e32 v3, v3, v114
	v_cndmask_b32_e32 v13, 0, v2, vcc
	v_add_f32_e32 v2, v117, v13
	v_add_f32_e32 v117, v2, v12
	ds_read_b32 v2, v212
	v_mul_f32_e32 v3, 0x3fb8aa3b, v3
	v_exp_f32_e32 v3, v3
	v_cmp_le_u32_e32 vcc, v151, v124
	v_cvt_pk_bf16_f32 v119, v13, v12
	s_waitcnt lgkmcnt(0)
	v_sub_f32_e32 v2, v2, v114
	v_mul_f32_e32 v2, 0x3fb8aa3b, v2
	v_exp_f32_e32 v2, v2
	s_nop 0
	v_pk_mul_f32 v[2:3], v[14:15], v[2:3]
	s_nop 0
	v_cndmask_b32_e32 v14, 0, v3, vcc
	v_cmp_le_u32_e32 vcc, v156, v124
	ds_read_b32 v3, v215
	s_waitcnt lgkmcnt(0)
	v_sub_f32_e32 v3, v3, v114
	v_cndmask_b32_e32 v15, 0, v2, vcc
	v_add_f32_e32 v2, v117, v15
	v_add_f32_e32 v117, v2, v14
	ds_read_b32 v2, v214
	v_mul_f32_e32 v3, 0x3fb8aa3b, v3
	v_exp_f32_e32 v3, v3
	v_cmp_le_u32_e32 vcc, v153, v124
	v_cvt_pk_bf16_f32 v120, v15, v14
	s_waitcnt lgkmcnt(0)
	v_sub_f32_e32 v2, v2, v114
	v_mul_f32_e32 v2, 0x3fb8aa3b, v2
	v_exp_f32_e32 v2, v2
	v_cvt_pk_bf16_f32 v114, v116, v115
	v_cvt_pk_bf16_f32 v115, v5, v4
	v_cvt_pk_bf16_f32 v116, v7, v6
	v_pk_mul_f32 v[2:3], v[16:17], v[2:3]
	s_nop 0
	v_cndmask_b32_e32 v3, 0, v3, vcc
	v_cmp_le_u32_e32 vcc, v158, v124
	s_nop 1
	v_cndmask_b32_e32 v2, 0, v2, vcc
	v_add_f32_e32 v16, v117, v2
	v_add_f32_e32 v166, v16, v3
	v_cvt_pk_bf16_f32 v117, v9, v8
	v_cvt_pk_bf16_f32 v121, v2, v3
	s_branch .LBB0_607

; __host__ __device__ __forceinline__ size_t blk(int r, int k, int K) { return (((size_t)((r >> 8) * (K >> 6) + (k >> 6))) << 14) + (size_t)(((r & 255) << 6) + (k & 63)); }
; __device__ __forceinline__ unsigned pk2(float lo, float hi) { f32x2 v = {lo, hi}; bf16x2_t b = __builtin_convertvector(v, bf16x2_t); return __builtin_bit_cast(unsigned, b); }
; __device__ __forceinline__ float fsilu(float x) { return x * fsigmoid(x); }
;     __device__ __forceinline__ void operator()(f32x4 (&acc)[2][2][4][2], const Unit& u, int wr, int wc, int fr, int fq) const { fused(acc, u, wr, wc, fr, fq, tb, wr * 4 + wc, fq * 16 + fr); }
;     __device__ __forceinline__ void operator()(const f32x4 (&acc)[2][2][4][2], const Unit& u, int wr, int wc, int fr, int fq) const {
;         const int row0 = u.pm * BM + wr * 64 + fr, col0 = u.pn * HALF + wc * 32 + 8 * fq;
; #pragma unroll
;         for (int ai = 0; ai < 2; ++ai)
; #pragma unroll
;             for (int m = 0; m < 4; ++m) { const int row = row0 + ai * HALF + m * 16; bf16_t* rowp = O + blk(row, col0, ldc);
;                 const float rs = ssq ? 1.0f / sqrtf(ssq[row] * (1.0f / D) + RMS_EPS) : 1.0f;
;                 const f32x4 a0 = acc[ai][0][m][0] * rs, a1 = acc[ai][0][m][1] * rs, b0 = acc[ai][1][m][0] * rs, b1 = acc[ai][1][m][1] * rs;
;                 u32x4 w; w.x = pk2(fsilu(a0[0]) * b0[0], fsilu(a0[1]) * b0[1]); w.y = pk2(fsilu(a0[2]) * b0[2], fsilu(a0[3]) * b0[3]);
;                 w.z = pk2(fsilu(a1[0]) * b1[0], fsilu(a1[1]) * b1[1]); w.w = pk2(fsilu(a1[2]) * b1[2], fsilu(a1[3]) * b1[3]);
;                 *(u32x4*)rowp = w; }
.LBB0_843:
	s_lshl_b32 s4, s4, 8
	s_add_i32 s4, s4, s48
	v_or_b32_e32 v150, s4, v195
	v_ashrrev_i32_e32 v151, 31, v150
	v_lshl_add_u64 v[148:149], v[150:151], 2, s[12:13]
	global_load_dword v138, v[148:149], off
	global_load_dword v175, v[148:149], off offset:64
	global_load_dword v176, v[148:149], off offset:128
	global_load_dword v177, v[148:149], off offset:192
	global_load_dword v180, v[148:149], off offset:512
	global_load_dword v181, v[148:149], off offset:576
	global_load_dword v182, v[148:149], off offset:640
	global_load_dword v183, v[148:149], off offset:704
	v_lshlrev_b32_e32 v151, 6, v150
	v_and_or_b32 v160, v151, s59, v152
	v_lshlrev_b32_e32 v170, 1, v160
	s_lshl_b32 s5, s5, 7
	s_or_b32 s5, s5, s49
	s_ashr_i32 s4, s4, 8
	v_or_b32_e32 v158, 16, v150
	s_ashr_i32 s17, s5, 6
	s_mulk_i32 s4, 0xac
	v_ashrrev_i32_e32 v159, 31, v158
	s_add_i32 s4, s4, s17
	s_ashr_i32 s5, s4, 31
	s_lshl_b64 s[40:41], s[4:5], 15
	s_add_u32 s40, s20, s40
	s_addc_u32 s41, s21, s41
	s_waitcnt vmcnt(0)
	v_fmamk_f32 v138, v138, 0x39800000, v156
	v_mul_f32_e32 v160, 0x4f800000, v138
	v_cmp_gt_f32_e32 vcc, s61, v138
	s_nop 1
	v_cndmask_b32_e32 v138, v138, v160, vcc
	v_sqrt_f32_e32 v162, v138
	v_lshl_add_u64 v[160:161], v[158:159], 2, s[12:13]
	v_add_u32_e32 v159, -1, v162
	v_add_u32_e32 v163, 1, v162
	v_fma_f32 v164, -v159, v162, v138
	v_fma_f32 v165, -v163, v162, v138
	v_cmp_ge_f32_e64 s[4:5], 0, v164
	s_nop 1
	v_cndmask_b32_e64 v159, v162, v159, s[4:5]
	v_cmp_lt_f32_e64 s[4:5], 0, v165
	s_nop 1
	v_cndmask_b32_e64 v159, v159, v163, s[4:5]
	v_mul_f32_e32 v162, 0x37800000, v159
	v_cndmask_b32_e32 v159, v159, v162, vcc
	v_cmp_class_f32_e32 vcc, v138, v157
	s_nop 1
	v_cndmask_b32_e32 v138, v159, v138, vcc
	v_div_scale_f32 v159, s[4:5], v138, v138, 1.0
	v_rcp_f32_e32 v162, v159
	v_div_scale_f32 v163, vcc, 1.0, v138, 1.0
	v_fma_f32 v164, -v159, v162, 1.0
	v_fmac_f32_e32 v162, v164, v162
	v_mul_f32_e32 v164, v163, v162
	v_fma_f32 v165, -v159, v164, v163
	v_fmac_f32_e32 v164, v165, v162
	v_fma_f32 v159, -v159, v164, v163
	v_div_fmas_f32 v159, v159, v162, v164
	v_div_fixup_f32 v138, v159, v138, 1.0
	v_pk_mul_f32 v[128:129], v[128:129], v[138:139] op_sel_hi:[1,0]
	v_pk_mul_f32 v[126:127], v[126:127], v[138:139] op_sel_hi:[1,0]
	v_pk_mul_f32 v[124:125], v[124:125], v[138:139] op_sel_hi:[1,0]
	v_pk_mul_f32 v[122:123], v[122:123], v[138:139] op_sel_hi:[1,0]
	v_pk_mul_f32 v[120:121], v[120:121], v[138:139] op_sel_hi:[1,0]
	v_pk_mul_f32 v[118:119], v[118:119], v[138:139] op_sel_hi:[1,0]
	v_pk_mul_f32 v[116:117], v[116:117], v[138:139] op_sel_hi:[1,0]
	v_pk_mul_f32 v[114:115], v[114:115], v[138:139] op_sel_hi:[1,0]
	v_mul_f32_e32 v138, 0xbfb8aa3b, v126
	v_mul_f32_e32 v159, 0xbfb8aa3b, v127
	v_mul_f32_e32 v162, 0xbfb8aa3b, v128
	v_mul_f32_e32 v163, 0xbfb8aa3b, v129
	v_mul_f32_e32 v164, 0xbfb8aa3b, v122
	v_mul_f32_e32 v165, 0xbfb8aa3b, v123
	v_mul_f32_e32 v166, 0xbfb8aa3b, v124
	v_mul_f32_e32 v167, 0xbfb8aa3b, v125
	v_exp_f32_e32 v138, v138
	v_exp_f32_e32 v159, v159
	v_exp_f32_e32 v162, v162
	v_exp_f32_e32 v163, v163
	v_exp_f32_e32 v164, v164
	v_exp_f32_e32 v165, v165
	v_exp_f32_e32 v166, v166
	v_exp_f32_e32 v167, v167
	v_add_f32_e32 v138, 1.0, v138
	v_add_f32_e32 v159, 1.0, v159
	v_add_f32_e32 v168, 1.0, v162
	v_add_f32_e32 v169, 1.0, v163
	v_add_f32_e32 v171, 1.0, v164
	v_add_f32_e32 v172, 1.0, v165
	v_add_f32_e32 v173, 1.0, v166
	v_add_f32_e32 v174, 1.0, v167
	v_rcp_f32_e32 v162, v138
	v_rcp_f32_e32 v163, v159
	v_rcp_f32_e32 v164, v168
	v_rcp_f32_e32 v165, v169
	v_rcp_f32_e32 v166, v171
	v_rcp_f32_e32 v167, v172
	v_rcp_f32_e32 v168, v173
	v_rcp_f32_e32 v169, v174
	v_pk_mul_f32 v[126:127], v[126:127], v[162:163]
	v_pk_mul_f32 v[128:129], v[128:129], v[164:165]
	v_pk_mul_f32 v[122:123], v[122:123], v[166:167]
	v_pk_mul_f32 v[124:125], v[124:125], v[168:169]
	v_pk_mul_f32 v[118:119], v[118:119], v[126:127]
	v_pk_mul_f32 v[120:121], v[120:121], v[128:129]
	v_pk_mul_f32 v[122:123], v[114:115], v[122:123]
	v_pk_mul_f32 v[124:125], v[116:117], v[124:125]
	v_cvt_pk_bf16_f32 v114, v118, v119
	v_cvt_pk_bf16_f32 v115, v120, v121
	v_cvt_pk_bf16_f32 v116, v122, v123
	v_cvt_pk_bf16_f32 v117, v124, v125
	global_store_dwordx4 v170, v[114:117], s[40:41]
	s_nop 0
	s_nop 0
	v_or_b32_e32 v114, 32, v150
	v_lshlrev_b32_e32 v116, 6, v158
	v_and_or_b32 v120, v116, s62, v152
	v_lshlrev_b32_e32 v126, 1, v120
	v_mov_b32_e32 v115, v175
	v_fmamk_f32 v115, v115, 0x39800000, v156
	v_mul_f32_e32 v117, 0x4f800000, v115
	v_cmp_gt_f32_e32 vcc, s61, v115
	s_nop 1
	v_cndmask_b32_e32 v118, v115, v117, vcc
	v_sqrt_f32_e32 v119, v118
	v_ashrrev_i32_e32 v115, 31, v114
	v_lshl_add_u64 v[116:117], v[114:115], 2, s[12:13]
	v_add_u32_e32 v115, -1, v119
	v_add_u32_e32 v121, 1, v119
	v_fma_f32 v122, -v115, v119, v118
	v_fma_f32 v123, -v121, v119, v118
	v_cmp_ge_f32_e64 s[4:5], 0, v122
	s_nop 1
	v_cndmask_b32_e64 v115, v119, v115, s[4:5]
	v_cmp_lt_f32_e64 s[4:5], 0, v123
	s_nop 1
	v_cndmask_b32_e64 v115, v115, v121, s[4:5]
	v_mul_f32_e32 v119, 0x37800000, v115
	v_cndmask_b32_e32 v115, v115, v119, vcc
	v_cmp_class_f32_e32 vcc, v118, v157
	s_nop 1
	v_cndmask_b32_e32 v115, v115, v118, vcc
	v_div_scale_f32 v118, s[4:5], v115, v115, 1.0
	v_rcp_f32_e32 v119, v118
	v_div_scale_f32 v120, vcc, 1.0, v115, 1.0
	v_fma_f32 v121, -v118, v119, 1.0
	v_fmac_f32_e32 v119, v121, v119
	v_mul_f32_e32 v121, v120, v119
	v_fma_f32 v122, -v118, v121, v120
	v_fmac_f32_e32 v121, v122, v119
	v_fma_f32 v118, -v118, v121, v120
	v_div_fmas_f32 v118, v118, v119, v121
	v_div_fixup_f32 v118, v118, v115, 1.0
	v_pk_mul_f32 v[112:113], v[112:113], v[118:119] op_sel_hi:[1,0]
	v_pk_mul_f32 v[110:111], v[110:111], v[118:119] op_sel_hi:[1,0]
; __host__ __device__ __forceinline__ size_t blk(int r, int k, int K) { return (((size_t)((r >> 8) * (K >> 6) + (k >> 6))) << 14) + (size_t)(((r & 255) << 6) + (k & 63)); }
; __device__ __forceinline__ unsigned pk2(float lo, float hi) { f32x2 v = {lo, hi}; bf16x2_t b = __builtin_convertvector(v, bf16x2_t); return __builtin_bit_cast(unsigned, b); }
; __device__ __forceinline__ float fsilu(float x) { return x * fsigmoid(x); }
;     __device__ __forceinline__ void operator()(f32x4 (&acc)[2][2][4][2], const Unit& u, int wr, int wc, int fr, int fq) const { fused(acc, u, wr, wc, fr, fq, tb, wr * 4 + wc, fq * 16 + fr); }
;     __device__ __forceinline__ void operator()(const f32x4 (&acc)[2][2][4][2], const Unit& u, int wr, int wc, int fr, int fq) const {
;         const int row0 = u.pm * BM + wr * 64 + fr, col0 = u.pn * HALF + wc * 32 + 8 * fq;
; #pragma unroll
;         for (int ai = 0; ai < 2; ++ai)
; #pragma unroll
;             for (int m = 0; m < 4; ++m) { const int row = row0 + ai * HALF + m * 16; bf16_t* rowp = O + blk(row, col0, ldc);
;                 const float rs = ssq ? 1.0f / sqrtf(ssq[row] * (1.0f / D) + RMS_EPS) : 1.0f;
;                 const f32x4 a0 = acc[ai][0][m][0] * rs, a1 = acc[ai][0][m][1] * rs, b0 = acc[ai][1][m][0] * rs, b1 = acc[ai][1][m][1] * rs;
;                 u32x4 w; w.x = pk2(fsilu(a0[0]) * b0[0], fsilu(a0[1]) * b0[1]); w.y = pk2(fsilu(a0[2]) * b0[2], fsilu(a0[3]) * b0[3]);
;                 w.z = pk2(fsilu(a1[0]) * b1[0], fsilu(a1[1]) * b1[1]); w.w = pk2(fsilu(a1[2]) * b1[2], fsilu(a1[3]) * b1[3]);
;                 *(u32x4*)rowp = w; }
	v_pk_mul_f32 v[108:109], v[108:109], v[118:119] op_sel_hi:[1,0]
	v_pk_mul_f32 v[106:107], v[106:107], v[118:119] op_sel_hi:[1,0]
	v_pk_mul_f32 v[104:105], v[104:105], v[118:119] op_sel_hi:[1,0]
	v_pk_mul_f32 v[102:103], v[102:103], v[118:119] op_sel_hi:[1,0]
	v_pk_mul_f32 v[100:101], v[100:101], v[118:119] op_sel_hi:[1,0]
	v_pk_mul_f32 v[98:99], v[98:99], v[118:119] op_sel_hi:[1,0]
	v_mul_f32_e32 v115, 0xbfb8aa3b, v110
	v_mul_f32_e32 v118, 0xbfb8aa3b, v111
	v_mul_f32_e32 v119, 0xbfb8aa3b, v112
	v_mul_f32_e32 v120, 0xbfb8aa3b, v113
	v_mul_f32_e32 v121, 0xbfb8aa3b, v106
	v_mul_f32_e32 v122, 0xbfb8aa3b, v107
	v_mul_f32_e32 v123, 0xbfb8aa3b, v108
	v_mul_f32_e32 v124, 0xbfb8aa3b, v109
	v_exp_f32_e32 v115, v115
	v_exp_f32_e32 v118, v118
	v_exp_f32_e32 v119, v119
	v_exp_f32_e32 v120, v120
	v_exp_f32_e32 v121, v121
	v_exp_f32_e32 v122, v122
	v_exp_f32_e32 v123, v123
	v_exp_f32_e32 v124, v124
	v_add_f32_e32 v115, 1.0, v115
	v_add_f32_e32 v125, 1.0, v118
	v_add_f32_e32 v127, 1.0, v119
	v_add_f32_e32 v128, 1.0, v120
	v_add_f32_e32 v129, 1.0, v121
	v_add_f32_e32 v138, 1.0, v122
	v_add_f32_e32 v158, 1.0, v123
	v_add_f32_e32 v159, 1.0, v124
	v_rcp_f32_e32 v118, v115
	v_rcp_f32_e32 v119, v125
	v_rcp_f32_e32 v120, v127
	v_rcp_f32_e32 v121, v128
	v_rcp_f32_e32 v122, v129
	v_rcp_f32_e32 v123, v138
	v_rcp_f32_e32 v124, v158
	v_rcp_f32_e32 v125, v159
	v_pk_mul_f32 v[110:111], v[110:111], v[118:119]
	v_pk_mul_f32 v[112:113], v[112:113], v[120:121]
	v_pk_mul_f32 v[106:107], v[106:107], v[122:123]
	v_pk_mul_f32 v[108:109], v[108:109], v[124:125]
	v_pk_mul_f32 v[102:103], v[102:103], v[110:111]
	v_pk_mul_f32 v[104:105], v[104:105], v[112:113]
	v_pk_mul_f32 v[106:107], v[98:99], v[106:107]
	v_pk_mul_f32 v[108:109], v[100:101], v[108:109]
	v_cvt_pk_bf16_f32 v98, v102, v103
	v_cvt_pk_bf16_f32 v99, v104, v105
	v_cvt_pk_bf16_f32 v100, v106, v107
	v_cvt_pk_bf16_f32 v101, v108, v109
	global_store_dwordx4 v126, v[98:101], s[40:41]
	s_nop 0
	s_nop 0
	v_or_b32_e32 v98, 48, v150
	v_lshlrev_b32_e32 v100, 6, v114
	v_and_or_b32 v104, v100, s63, v152
	v_lshlrev_b32_e32 v110, 1, v104
	v_mov_b32_e32 v99, v176
	v_fmamk_f32 v99, v99, 0x39800000, v156
	v_mul_f32_e32 v101, 0x4f800000, v99
	v_cmp_gt_f32_e32 vcc, s61, v99
	s_nop 1
	v_cndmask_b32_e32 v102, v99, v101, vcc
	v_sqrt_f32_e32 v103, v102
	v_ashrrev_i32_e32 v99, 31, v98
	v_lshl_add_u64 v[100:101], v[98:99], 2, s[12:13]
	v_add_u32_e32 v99, -1, v103
	v_add_u32_e32 v105, 1, v103
	v_fma_f32 v106, -v99, v103, v102
	v_fma_f32 v107, -v105, v103, v102
	v_cmp_ge_f32_e64 s[4:5], 0, v106
	s_nop 1
	v_cndmask_b32_e64 v99, v103, v99, s[4:5]
	v_cmp_lt_f32_e64 s[4:5], 0, v107
	s_nop 1
	v_cndmask_b32_e64 v99, v99, v105, s[4:5]
	v_mul_f32_e32 v103, 0x37800000, v99
	v_cndmask_b32_e32 v99, v99, v103, vcc
	v_cmp_class_f32_e32 vcc, v102, v157
	s_nop 1
	v_cndmask_b32_e32 v99, v99, v102, vcc
	v_div_scale_f32 v102, s[4:5], v99, v99, 1.0
	v_rcp_f32_e32 v103, v102
	v_div_scale_f32 v104, vcc, 1.0, v99, 1.0
	v_fma_f32 v105, -v102, v103, 1.0
	v_fmac_f32_e32 v103, v105, v103
	v_mul_f32_e32 v105, v104, v103
	v_fma_f32 v106, -v102, v105, v104
	v_fmac_f32_e32 v105, v106, v103
	v_fma_f32 v102, -v102, v105, v104
	v_div_fmas_f32 v102, v102, v103, v105
	v_div_fixup_f32 v102, v102, v99, 1.0
	v_pk_mul_f32 v[96:97], v[96:97], v[102:103] op_sel_hi:[1,0]
	v_pk_mul_f32 v[94:95], v[94:95], v[102:103] op_sel_hi:[1,0]
	v_pk_mul_f32 v[92:93], v[92:93], v[102:103] op_sel_hi:[1,0]
	v_pk_mul_f32 v[90:91], v[90:91], v[102:103] op_sel_hi:[1,0]
	v_pk_mul_f32 v[88:89], v[88:89], v[102:103] op_sel_hi:[1,0]
	v_pk_mul_f32 v[86:87], v[86:87], v[102:103] op_sel_hi:[1,0]
	v_pk_mul_f32 v[84:85], v[84:85], v[102:103] op_sel_hi:[1,0]
	v_pk_mul_f32 v[82:83], v[82:83], v[102:103] op_sel_hi:[1,0]
	v_mul_f32_e32 v99, 0xbfb8aa3b, v94
	v_mul_f32_e32 v102, 0xbfb8aa3b, v95
	v_mul_f32_e32 v103, 0xbfb8aa3b, v96
	v_mul_f32_e32 v104, 0xbfb8aa3b, v97
	v_mul_f32_e32 v105, 0xbfb8aa3b, v90
	v_mul_f32_e32 v106, 0xbfb8aa3b, v91
	v_mul_f32_e32 v107, 0xbfb8aa3b, v92
	v_mul_f32_e32 v108, 0xbfb8aa3b, v93
	v_exp_f32_e32 v99, v99
	v_exp_f32_e32 v102, v102
	v_exp_f32_e32 v103, v103
	v_exp_f32_e32 v104, v104
	v_exp_f32_e32 v105, v105
	v_exp_f32_e32 v106, v106
	v_exp_f32_e32 v107, v107
	v_exp_f32_e32 v108, v108
	v_add_f32_e32 v99, 1.0, v99
	v_add_f32_e32 v109, 1.0, v102
	v_add_f32_e32 v111, 1.0, v103
	v_add_f32_e32 v112, 1.0, v104
	v_add_f32_e32 v113, 1.0, v105
	v_add_f32_e32 v114, 1.0, v106
	v_add_f32_e32 v115, 1.0, v107
	v_add_f32_e32 v116, 1.0, v108
	v_rcp_f32_e32 v102, v99
	v_rcp_f32_e32 v103, v109
	v_rcp_f32_e32 v104, v111
	v_rcp_f32_e32 v105, v112
	v_rcp_f32_e32 v106, v113
	v_rcp_f32_e32 v107, v114
	v_rcp_f32_e32 v108, v115
	v_rcp_f32_e32 v109, v116
	v_pk_mul_f32 v[94:95], v[94:95], v[102:103]
	v_pk_mul_f32 v[96:97], v[96:97], v[104:105]
	v_pk_mul_f32 v[90:91], v[90:91], v[106:107]
	v_pk_mul_f32 v[92:93], v[92:93], v[108:109]
	v_pk_mul_f32 v[86:87], v[86:87], v[94:95]
	v_pk_mul_f32 v[88:89], v[88:89], v[96:97]
	v_pk_mul_f32 v[90:91], v[82:83], v[90:91]
	v_pk_mul_f32 v[92:93], v[84:85], v[92:93]
	v_cvt_pk_bf16_f32 v82, v86, v87
	v_cvt_pk_bf16_f32 v83, v88, v89
	v_cvt_pk_bf16_f32 v84, v90, v91
	v_cvt_pk_bf16_f32 v85, v92, v93
	global_store_dwordx4 v110, v[82:85], s[40:41]
	s_nop 0
	s_nop 0
	v_lshlrev_b32_e32 v84, 6, v98
	v_and_or_b32 v84, v84, s64, v152
	v_lshlrev_b32_e32 v90, 1, v84
	v_mov_b32_e32 v82, v177
	v_fmamk_f32 v82, v82, 0x39800000, v156
	v_mul_f32_e32 v83, 0x4f800000, v82
	v_cmp_gt_f32_e32 vcc, s61, v82
	s_nop 1
	v_cndmask_b32_e32 v82, v82, v83, vcc
	v_sqrt_f32_e32 v83, v82
	s_nop 0
	v_add_u32_e32 v85, -1, v83
	v_add_u32_e32 v86, 1, v83
	v_fma_f32 v87, -v85, v83, v82
	v_fma_f32 v88, -v86, v83, v82
; __host__ __device__ __forceinline__ size_t blk(int r, int k, int K) { return (((size_t)((r >> 8) * (K >> 6) + (k >> 6))) << 14) + (size_t)(((r & 255) << 6) + (k & 63)); }
; __device__ __forceinline__ unsigned pk2(float lo, float hi) { f32x2 v = {lo, hi}; bf16x2_t b = __builtin_convertvector(v, bf16x2_t); return __builtin_bit_cast(unsigned, b); }
; __device__ __forceinline__ float fsilu(float x) { return x * fsigmoid(x); }
;     __device__ __forceinline__ void operator()(f32x4 (&acc)[2][2][4][2], const Unit& u, int wr, int wc, int fr, int fq) const { fused(acc, u, wr, wc, fr, fq, tb, wr * 4 + wc, fq * 16 + fr); }
;     __device__ __forceinline__ void operator()(const f32x4 (&acc)[2][2][4][2], const Unit& u, int wr, int wc, int fr, int fq) const {
;         const int row0 = u.pm * BM + wr * 64 + fr, col0 = u.pn * HALF + wc * 32 + 8 * fq;
; #pragma unroll
;         for (int ai = 0; ai < 2; ++ai)
; #pragma unroll
;             for (int m = 0; m < 4; ++m) { const int row = row0 + ai * HALF + m * 16; bf16_t* rowp = O + blk(row, col0, ldc);
;                 const float rs = ssq ? 1.0f / sqrtf(ssq[row] * (1.0f / D) + RMS_EPS) : 1.0f;
;                 const f32x4 a0 = acc[ai][0][m][0] * rs, a1 = acc[ai][0][m][1] * rs, b0 = acc[ai][1][m][0] * rs, b1 = acc[ai][1][m][1] * rs;
;                 u32x4 w; w.x = pk2(fsilu(a0[0]) * b0[0], fsilu(a0[1]) * b0[1]); w.y = pk2(fsilu(a0[2]) * b0[2], fsilu(a0[3]) * b0[3]);
;                 w.z = pk2(fsilu(a1[0]) * b1[0], fsilu(a1[1]) * b1[1]); w.w = pk2(fsilu(a1[2]) * b1[2], fsilu(a1[3]) * b1[3]);
;                 *(u32x4*)rowp = w; }
	v_cmp_ge_f32_e64 s[4:5], 0, v87
	s_nop 1
	v_cndmask_b32_e64 v83, v83, v85, s[4:5]
	v_cmp_lt_f32_e64 s[4:5], 0, v88
	s_nop 1
	v_cndmask_b32_e64 v83, v83, v86, s[4:5]
	v_mul_f32_e32 v85, 0x37800000, v83
	v_cndmask_b32_e32 v83, v83, v85, vcc
	v_cmp_class_f32_e32 vcc, v82, v157
	s_nop 1
	v_cndmask_b32_e32 v82, v83, v82, vcc
	v_div_scale_f32 v83, s[4:5], v82, v82, 1.0
	v_rcp_f32_e32 v85, v83
	v_div_scale_f32 v84, vcc, 1.0, v82, 1.0
	v_fma_f32 v86, -v83, v85, 1.0
	v_fmac_f32_e32 v85, v86, v85
	v_mul_f32_e32 v86, v84, v85
	v_fma_f32 v87, -v83, v86, v84
	v_fmac_f32_e32 v86, v87, v85
	v_fma_f32 v83, -v83, v86, v84
	v_div_fmas_f32 v83, v83, v85, v86
	v_div_fixup_f32 v82, v83, v82, 1.0
	v_pk_mul_f32 v[80:81], v[80:81], v[82:83] op_sel_hi:[1,0]
	v_pk_mul_f32 v[78:79], v[78:79], v[82:83] op_sel_hi:[1,0]
	v_pk_mul_f32 v[76:77], v[76:77], v[82:83] op_sel_hi:[1,0]
	v_pk_mul_f32 v[74:75], v[74:75], v[82:83] op_sel_hi:[1,0]
	v_pk_mul_f32 v[72:73], v[72:73], v[82:83] op_sel_hi:[1,0]
	v_pk_mul_f32 v[70:71], v[70:71], v[82:83] op_sel_hi:[1,0]
	v_pk_mul_f32 v[68:69], v[68:69], v[82:83] op_sel_hi:[1,0]
	v_pk_mul_f32 v[66:67], v[66:67], v[82:83] op_sel_hi:[1,0]
	v_mul_f32_e32 v82, 0xbfb8aa3b, v78
	v_mul_f32_e32 v83, 0xbfb8aa3b, v79
	v_mul_f32_e32 v84, 0xbfb8aa3b, v80
	v_mul_f32_e32 v85, 0xbfb8aa3b, v81
	v_mul_f32_e32 v86, 0xbfb8aa3b, v74
	v_mul_f32_e32 v87, 0xbfb8aa3b, v75
	v_mul_f32_e32 v88, 0xbfb8aa3b, v76
	v_mul_f32_e32 v89, 0xbfb8aa3b, v77
	v_exp_f32_e32 v82, v82
	v_exp_f32_e32 v83, v83
	v_exp_f32_e32 v84, v84
	v_exp_f32_e32 v85, v85
	v_exp_f32_e32 v86, v86
	v_exp_f32_e32 v87, v87
	v_exp_f32_e32 v88, v88
	v_exp_f32_e32 v89, v89
	v_add_f32_e32 v82, 1.0, v82
	v_add_f32_e32 v83, 1.0, v83
	v_add_f32_e32 v84, 1.0, v84
	v_add_f32_e32 v85, 1.0, v85
	v_add_f32_e32 v86, 1.0, v86
	v_add_f32_e32 v87, 1.0, v87
	v_add_f32_e32 v88, 1.0, v88
	v_add_f32_e32 v89, 1.0, v89
	v_rcp_f32_e32 v82, v82
	v_rcp_f32_e32 v83, v83
	v_rcp_f32_e32 v84, v84
	v_rcp_f32_e32 v85, v85
	v_rcp_f32_e32 v86, v86
	v_rcp_f32_e32 v87, v87
	v_rcp_f32_e32 v88, v88
	v_rcp_f32_e32 v89, v89
	v_pk_mul_f32 v[78:79], v[78:79], v[82:83]
	v_pk_mul_f32 v[80:81], v[80:81], v[84:85]
	v_pk_mul_f32 v[74:75], v[74:75], v[86:87]
	v_pk_mul_f32 v[76:77], v[76:77], v[88:89]
	v_pk_mul_f32 v[70:71], v[70:71], v[78:79]
	v_pk_mul_f32 v[72:73], v[72:73], v[80:81]
	v_pk_mul_f32 v[74:75], v[66:67], v[74:75]
	v_pk_mul_f32 v[76:77], v[68:69], v[76:77]
	v_cvt_pk_bf16_f32 v66, v70, v71
	v_cvt_pk_bf16_f32 v67, v72, v73
	v_cvt_pk_bf16_f32 v68, v74, v75
	v_cvt_pk_bf16_f32 v69, v76, v77
	global_store_dwordx4 v90, v[66:69], s[40:41]
	s_nop 0
	s_nop 0
	v_add_u32_e32 v66, 0x80, v150
	v_mov_b32_e32 v67, s17
	v_lshrrev_b32_e32 v69, 8, v66
	v_lshlrev_b32_e32 v70, 6, v66
	v_mad_i32_i24 v66, v69, s58, v67
	v_and_or_b32 v69, v70, s59, v152
	v_lshlrev_b32_e32 v138, 1, v69
	v_ashrrev_i32_e32 v67, 31, v66
	v_lshlrev_b64 v[66:67], 15, v[66:67]
	v_lshl_add_u64 v[66:67], s[20:21], 0, v[66:67]
	v_mov_b32_e32 v68, v180
	v_fmamk_f32 v68, v68, 0x39800000, v156
	v_mul_f32_e32 v70, 0x4f800000, v68
	v_cmp_gt_f32_e32 vcc, s61, v68
	s_nop 1
	v_cndmask_b32_e32 v68, v68, v70, vcc
	v_sqrt_f32_e32 v70, v68
	s_nop 0
	v_add_u32_e32 v69, -1, v70
	v_add_u32_e32 v71, 1, v70
	v_fma_f32 v72, -v69, v70, v68
	v_fma_f32 v73, -v71, v70, v68
	v_cmp_ge_f32_e64 s[4:5], 0, v72
	s_nop 1
	v_cndmask_b32_e64 v69, v70, v69, s[4:5]
	v_cmp_lt_f32_e64 s[4:5], 0, v73
	s_nop 1
	v_cndmask_b32_e64 v69, v69, v71, s[4:5]
	v_mul_f32_e32 v70, 0x37800000, v69
	v_cndmask_b32_e32 v69, v69, v70, vcc
	v_cmp_class_f32_e32 vcc, v68, v157
	s_nop 1
	v_cndmask_b32_e32 v70, v69, v68, vcc
	v_div_scale_f32 v71, s[4:5], v70, v70, 1.0
	v_rcp_f32_e32 v72, v71
	v_div_scale_f32 v73, vcc, 1.0, v70, 1.0
	v_lshl_add_u64 v[68:69], v[66:67], 0, v[138:139]
	v_fma_f32 v74, -v71, v72, 1.0
	v_fmac_f32_e32 v72, v74, v72
	v_mul_f32_e32 v74, v73, v72
	v_fma_f32 v75, -v71, v74, v73
	v_fmac_f32_e32 v74, v75, v72
	v_fma_f32 v71, -v71, v74, v73
	v_div_fmas_f32 v71, v71, v72, v74
	v_div_fixup_f32 v70, v71, v70, 1.0
	v_pk_mul_f32 v[64:65], v[64:65], v[70:71] op_sel_hi:[1,0]
	v_pk_mul_f32 v[62:63], v[62:63], v[70:71] op_sel_hi:[1,0]
	v_pk_mul_f32 v[60:61], v[60:61], v[70:71] op_sel_hi:[1,0]
	v_pk_mul_f32 v[58:59], v[58:59], v[70:71] op_sel_hi:[1,0]
	v_pk_mul_f32 v[56:57], v[56:57], v[70:71] op_sel_hi:[1,0]
	v_pk_mul_f32 v[54:55], v[54:55], v[70:71] op_sel_hi:[1,0]
	v_pk_mul_f32 v[52:53], v[52:53], v[70:71] op_sel_hi:[1,0]
	v_pk_mul_f32 v[50:51], v[50:51], v[70:71] op_sel_hi:[1,0]
	v_mul_f32_e32 v70, 0xbfb8aa3b, v62
	v_mul_f32_e32 v71, 0xbfb8aa3b, v63
	v_mul_f32_e32 v72, 0xbfb8aa3b, v64
	v_mul_f32_e32 v73, 0xbfb8aa3b, v65
	v_mul_f32_e32 v74, 0xbfb8aa3b, v58
	v_mul_f32_e32 v75, 0xbfb8aa3b, v59
	v_mul_f32_e32 v76, 0xbfb8aa3b, v60
	v_mul_f32_e32 v77, 0xbfb8aa3b, v61
	v_exp_f32_e32 v70, v70
	v_exp_f32_e32 v71, v71
	v_exp_f32_e32 v72, v72
	v_exp_f32_e32 v73, v73
	v_exp_f32_e32 v74, v74
	v_exp_f32_e32 v75, v75
	v_exp_f32_e32 v76, v76
	v_exp_f32_e32 v77, v77
	v_add_f32_e32 v70, 1.0, v70
	v_add_f32_e32 v71, 1.0, v71
	v_add_f32_e32 v72, 1.0, v72
	v_add_f32_e32 v73, 1.0, v73
	v_add_f32_e32 v74, 1.0, v74
	v_add_f32_e32 v75, 1.0, v75
	v_add_f32_e32 v76, 1.0, v76
	v_add_f32_e32 v77, 1.0, v77
	v_rcp_f32_e32 v70, v70
	v_rcp_f32_e32 v71, v71
	v_rcp_f32_e32 v72, v72
	v_rcp_f32_e32 v73, v73
	v_rcp_f32_e32 v74, v74
	v_rcp_f32_e32 v75, v75
	v_rcp_f32_e32 v76, v76
	v_rcp_f32_e32 v77, v77
	v_pk_mul_f32 v[62:63], v[62:63], v[70:71]
	v_pk_mul_f32 v[64:65], v[64:65], v[72:73]
	v_pk_mul_f32 v[58:59], v[58:59], v[74:75]
	v_pk_mul_f32 v[60:61], v[60:61], v[76:77]
	v_pk_mul_f32 v[54:55], v[54:55], v[62:63]
	v_pk_mul_f32 v[56:57], v[56:57], v[64:65]
; __host__ __device__ __forceinline__ size_t blk(int r, int k, int K) { return (((size_t)((r >> 8) * (K >> 6) + (k >> 6))) << 14) + (size_t)(((r & 255) << 6) + (k & 63)); }
; __device__ __forceinline__ unsigned pk2(float lo, float hi) { f32x2 v = {lo, hi}; bf16x2_t b = __builtin_convertvector(v, bf16x2_t); return __builtin_bit_cast(unsigned, b); }
; __device__ __forceinline__ float fsilu(float x) { return x * fsigmoid(x); }
;     __device__ __forceinline__ void operator()(f32x4 (&acc)[2][2][4][2], const Unit& u, int wr, int wc, int fr, int fq) const { fused(acc, u, wr, wc, fr, fq, tb, wr * 4 + wc, fq * 16 + fr); }
;     __device__ __forceinline__ void operator()(const f32x4 (&acc)[2][2][4][2], const Unit& u, int wr, int wc, int fr, int fq) const {
;         const int row0 = u.pm * BM + wr * 64 + fr, col0 = u.pn * HALF + wc * 32 + 8 * fq;
; #pragma unroll
;         for (int ai = 0; ai < 2; ++ai)
; #pragma unroll
;             for (int m = 0; m < 4; ++m) { const int row = row0 + ai * HALF + m * 16; bf16_t* rowp = O + blk(row, col0, ldc);
;                 const float rs = ssq ? 1.0f / sqrtf(ssq[row] * (1.0f / D) + RMS_EPS) : 1.0f;
;                 const f32x4 a0 = acc[ai][0][m][0] * rs, a1 = acc[ai][0][m][1] * rs, b0 = acc[ai][1][m][0] * rs, b1 = acc[ai][1][m][1] * rs;
;                 u32x4 w; w.x = pk2(fsilu(a0[0]) * b0[0], fsilu(a0[1]) * b0[1]); w.y = pk2(fsilu(a0[2]) * b0[2], fsilu(a0[3]) * b0[3]);
;                 w.z = pk2(fsilu(a1[0]) * b1[0], fsilu(a1[1]) * b1[1]); w.w = pk2(fsilu(a1[2]) * b1[2], fsilu(a1[3]) * b1[3]);
;                 *(u32x4*)rowp = w; }
	v_pk_mul_f32 v[58:59], v[50:51], v[58:59]
	v_pk_mul_f32 v[60:61], v[52:53], v[60:61]
	v_cvt_pk_bf16_f32 v50, v54, v55
	v_cvt_pk_bf16_f32 v51, v56, v57
	v_cvt_pk_bf16_f32 v52, v58, v59
	v_cvt_pk_bf16_f32 v53, v60, v61
	global_store_dwordx4 v[68:69], v[50:53], off
	s_nop 0
	s_nop 0
	v_add_u32_e32 v52, 0x2400, v151
	v_and_or_b32 v52, v52, s62, v152
	v_lshlrev_b32_e32 v138, 1, v52
	v_mov_b32_e32 v50, v181
	v_fmamk_f32 v50, v50, 0x39800000, v156
	v_mul_f32_e32 v51, 0x4f800000, v50
	v_cmp_gt_f32_e32 vcc, s61, v50
	s_nop 1
	v_cndmask_b32_e32 v50, v50, v51, vcc
	v_sqrt_f32_e32 v51, v50
	s_nop 0
	v_add_u32_e32 v52, -1, v51
	v_add_u32_e32 v53, 1, v51
	v_fma_f32 v54, -v52, v51, v50
	v_fma_f32 v55, -v53, v51, v50
	v_cmp_ge_f32_e64 s[4:5], 0, v54
	s_nop 1
	v_cndmask_b32_e64 v51, v51, v52, s[4:5]
	v_cmp_lt_f32_e64 s[4:5], 0, v55
	s_nop 1
	v_cndmask_b32_e64 v51, v51, v53, s[4:5]
	v_mul_f32_e32 v52, 0x37800000, v51
	v_cndmask_b32_e32 v51, v51, v52, vcc
	v_cmp_class_f32_e32 vcc, v50, v157
	s_nop 1
	v_cndmask_b32_e32 v52, v51, v50, vcc
	v_div_scale_f32 v53, s[4:5], v52, v52, 1.0
	v_rcp_f32_e32 v54, v53
	v_div_scale_f32 v55, vcc, 1.0, v52, 1.0
	v_lshl_add_u64 v[50:51], v[66:67], 0, v[138:139]
	v_fma_f32 v56, -v53, v54, 1.0
	v_fmac_f32_e32 v54, v56, v54
	v_mul_f32_e32 v56, v55, v54
	v_fma_f32 v57, -v53, v56, v55
	v_fmac_f32_e32 v56, v57, v54
	v_fma_f32 v53, -v53, v56, v55
	v_div_fmas_f32 v53, v53, v54, v56
	v_div_fixup_f32 v52, v53, v52, 1.0
	v_pk_mul_f32 v[48:49], v[48:49], v[52:53] op_sel_hi:[1,0]
	v_pk_mul_f32 v[46:47], v[46:47], v[52:53] op_sel_hi:[1,0]
	v_pk_mul_f32 v[44:45], v[44:45], v[52:53] op_sel_hi:[1,0]
	v_pk_mul_f32 v[42:43], v[42:43], v[52:53] op_sel_hi:[1,0]
	v_pk_mul_f32 v[40:41], v[40:41], v[52:53] op_sel_hi:[1,0]
	v_pk_mul_f32 v[38:39], v[38:39], v[52:53] op_sel_hi:[1,0]
	v_pk_mul_f32 v[36:37], v[36:37], v[52:53] op_sel_hi:[1,0]
	v_pk_mul_f32 v[34:35], v[34:35], v[52:53] op_sel_hi:[1,0]
	v_mul_f32_e32 v52, 0xbfb8aa3b, v46
	v_mul_f32_e32 v53, 0xbfb8aa3b, v47
	v_mul_f32_e32 v54, 0xbfb8aa3b, v48
	v_mul_f32_e32 v55, 0xbfb8aa3b, v49
	v_mul_f32_e32 v56, 0xbfb8aa3b, v42
	v_mul_f32_e32 v57, 0xbfb8aa3b, v43
	v_mul_f32_e32 v58, 0xbfb8aa3b, v44
	v_mul_f32_e32 v59, 0xbfb8aa3b, v45
	v_exp_f32_e32 v52, v52
	v_exp_f32_e32 v53, v53
	v_exp_f32_e32 v54, v54
	v_exp_f32_e32 v55, v55
	v_exp_f32_e32 v56, v56
	v_exp_f32_e32 v57, v57
	v_exp_f32_e32 v58, v58
	v_exp_f32_e32 v59, v59
	v_add_f32_e32 v52, 1.0, v52
	v_add_f32_e32 v53, 1.0, v53
	v_add_f32_e32 v54, 1.0, v54
	v_add_f32_e32 v55, 1.0, v55
	v_add_f32_e32 v56, 1.0, v56
	v_add_f32_e32 v57, 1.0, v57
	v_add_f32_e32 v58, 1.0, v58
	v_add_f32_e32 v59, 1.0, v59
	v_rcp_f32_e32 v52, v52
	v_rcp_f32_e32 v53, v53
	v_rcp_f32_e32 v54, v54
	v_rcp_f32_e32 v55, v55
	v_rcp_f32_e32 v56, v56
	v_rcp_f32_e32 v57, v57
	v_rcp_f32_e32 v58, v58
	v_rcp_f32_e32 v59, v59
	v_pk_mul_f32 v[46:47], v[46:47], v[52:53]
	v_pk_mul_f32 v[48:49], v[48:49], v[54:55]
	v_pk_mul_f32 v[42:43], v[42:43], v[56:57]
	v_pk_mul_f32 v[44:45], v[44:45], v[58:59]
	v_pk_mul_f32 v[38:39], v[38:39], v[46:47]
	v_pk_mul_f32 v[40:41], v[40:41], v[48:49]
	v_pk_mul_f32 v[42:43], v[34:35], v[42:43]
	v_pk_mul_f32 v[44:45], v[36:37], v[44:45]
	v_cvt_pk_bf16_f32 v34, v38, v39
	v_cvt_pk_bf16_f32 v35, v40, v41
	v_cvt_pk_bf16_f32 v36, v42, v43
	v_cvt_pk_bf16_f32 v37, v44, v45
	global_store_dwordx4 v[50:51], v[34:37], off
	s_nop 0
	s_nop 0
	v_add_u32_e32 v36, 0x2800, v151
	v_and_or_b32 v36, v36, s63, v152
	v_lshlrev_b32_e32 v138, 1, v36
	v_mov_b32_e32 v34, v182
	v_fmamk_f32 v34, v34, 0x39800000, v156
	v_mul_f32_e32 v35, 0x4f800000, v34
	v_cmp_gt_f32_e32 vcc, s61, v34
	s_nop 1
	v_cndmask_b32_e32 v34, v34, v35, vcc
	v_sqrt_f32_e32 v35, v34
	s_nop 0
	v_add_u32_e32 v36, -1, v35
	v_add_u32_e32 v37, 1, v35
	v_fma_f32 v38, -v36, v35, v34
	v_fma_f32 v39, -v37, v35, v34
	v_cmp_ge_f32_e64 s[4:5], 0, v38
	s_nop 1
	v_cndmask_b32_e64 v35, v35, v36, s[4:5]
	v_cmp_lt_f32_e64 s[4:5], 0, v39
	s_nop 1
	v_cndmask_b32_e64 v35, v35, v37, s[4:5]
	v_mul_f32_e32 v36, 0x37800000, v35
	v_cndmask_b32_e32 v35, v35, v36, vcc
	v_cmp_class_f32_e32 vcc, v34, v157
	s_nop 1
	v_cndmask_b32_e32 v36, v35, v34, vcc
	v_div_scale_f32 v37, s[4:5], v36, v36, 1.0
	v_rcp_f32_e32 v38, v37
	v_div_scale_f32 v39, vcc, 1.0, v36, 1.0
	v_lshl_add_u64 v[34:35], v[66:67], 0, v[138:139]
	v_fma_f32 v40, -v37, v38, 1.0
	v_fmac_f32_e32 v38, v40, v38
	v_mul_f32_e32 v40, v39, v38
	v_fma_f32 v41, -v37, v40, v39
	v_fmac_f32_e32 v40, v41, v38
	v_fma_f32 v37, -v37, v40, v39
	v_div_fmas_f32 v37, v37, v38, v40
	v_div_fixup_f32 v36, v37, v36, 1.0
	v_pk_mul_f32 v[32:33], v[32:33], v[36:37] op_sel_hi:[1,0]
	v_pk_mul_f32 v[30:31], v[30:31], v[36:37] op_sel_hi:[1,0]
	v_pk_mul_f32 v[28:29], v[28:29], v[36:37] op_sel_hi:[1,0]
	v_pk_mul_f32 v[26:27], v[26:27], v[36:37] op_sel_hi:[1,0]
	v_pk_mul_f32 v[24:25], v[24:25], v[36:37] op_sel_hi:[1,0]
; __host__ __device__ __forceinline__ size_t blk(int r, int k, int K) { return (((size_t)((r >> 8) * (K >> 6) + (k >> 6))) << 14) + (size_t)(((r & 255) << 6) + (k & 63)); }
; __device__ __forceinline__ unsigned pk2(float lo, float hi) { f32x2 v = {lo, hi}; bf16x2_t b = __builtin_convertvector(v, bf16x2_t); return __builtin_bit_cast(unsigned, b); }
; __device__ __forceinline__ float fsilu(float x) { return x * fsigmoid(x); }
; #define PG8_BAR __builtin_amdgcn_s_barrier()
;     __device__ __forceinline__ void operator()(const f32x4 (&acc)[2][2][4][2], const Unit& u, int wr, int wc, int fr, int fq) const {
;     ...
;             for (int m = 0; m < 4; ++m) { const int row = row0 + ai * HALF + m * 16; bf16_t* rowp = O + blk(row, col0, ldc);
;                 const float rs = ssq ? 1.0f / sqrtf(ssq[row] * (1.0f / D) + RMS_EPS) : 1.0f;
;                 const f32x4 a0 = acc[ai][0][m][0] * rs, a1 = acc[ai][0][m][1] * rs, b0 = acc[ai][1][m][0] * rs, b1 = acc[ai][1][m][1] * rs;
;                 u32x4 w; w.x = pk2(fsilu(a0[0]) * b0[0], fsilu(a0[1]) * b0[1]); w.y = pk2(fsilu(a0[2]) * b0[2], fsilu(a0[3]) * b0[3]);
;                 w.z = pk2(fsilu(a1[0]) * b1[0], fsilu(a1[1]) * b1[1]); w.w = pk2(fsilu(a1[2]) * b1[2], fsilu(a1[3]) * b1[3]);
;                 *(u32x4*)rowp = w; }
; template <class Epi, class Sched, bool ALIGN_EPI = false, bool SP2 = false>
; __device__ __forceinline__ void gemm_phase(PG8_LAS unsigned char* lds, const Gemm g, const Sched& S, const Epi& E) {
;     ...
;         if constexpr (!Epi::AFTER_DRAIN) { E(acc, cur, wr, wc, fr, fq); S.done(cur); }
;         if (!has_next) break;
; #pragma unroll
;         for (int a = 0; a < 2; ++a)
; #pragma unroll
;             for (int b = 0; b < 2; ++b)
; #pragma unroll
;                 for (int m = 0; m < 4; ++m)
; #pragma unroll
;                     for (int n = 0; n < 2; ++n) acc[a][b][m][n] = (f32x4){0.f, 0.f, 0.f, 0.f};
;         cur = nxt; cA = nA; cB = nB; ++ui;
;         if constexpr (ALIGN_EPI) { if (wr == 1) PG8_BAR; }
	v_pk_mul_f32 v[22:23], v[22:23], v[36:37] op_sel_hi:[1,0]
	v_pk_mul_f32 v[20:21], v[20:21], v[36:37] op_sel_hi:[1,0]
	v_pk_mul_f32 v[18:19], v[18:19], v[36:37] op_sel_hi:[1,0]
	v_mul_f32_e32 v36, 0xbfb8aa3b, v30
	v_mul_f32_e32 v37, 0xbfb8aa3b, v31
	v_mul_f32_e32 v38, 0xbfb8aa3b, v32
	v_mul_f32_e32 v39, 0xbfb8aa3b, v33
	v_mul_f32_e32 v40, 0xbfb8aa3b, v26
	v_mul_f32_e32 v41, 0xbfb8aa3b, v27
	v_mul_f32_e32 v42, 0xbfb8aa3b, v28
	v_mul_f32_e32 v43, 0xbfb8aa3b, v29
	v_exp_f32_e32 v36, v36
	v_exp_f32_e32 v37, v37
	v_exp_f32_e32 v38, v38
	v_exp_f32_e32 v39, v39
	v_exp_f32_e32 v40, v40
	v_exp_f32_e32 v41, v41
	v_exp_f32_e32 v42, v42
	v_exp_f32_e32 v43, v43
	v_add_f32_e32 v36, 1.0, v36
	v_add_f32_e32 v37, 1.0, v37
	v_add_f32_e32 v38, 1.0, v38
	v_add_f32_e32 v39, 1.0, v39
	v_add_f32_e32 v40, 1.0, v40
	v_add_f32_e32 v41, 1.0, v41
	v_add_f32_e32 v42, 1.0, v42
	v_add_f32_e32 v43, 1.0, v43
	v_rcp_f32_e32 v36, v36
	v_rcp_f32_e32 v37, v37
	v_rcp_f32_e32 v38, v38
	v_rcp_f32_e32 v39, v39
	v_rcp_f32_e32 v40, v40
	v_rcp_f32_e32 v41, v41
	v_rcp_f32_e32 v42, v42
	v_rcp_f32_e32 v43, v43
	v_pk_mul_f32 v[30:31], v[30:31], v[36:37]
	v_pk_mul_f32 v[32:33], v[32:33], v[38:39]
	v_pk_mul_f32 v[26:27], v[26:27], v[40:41]
	v_pk_mul_f32 v[28:29], v[28:29], v[42:43]
	v_pk_mul_f32 v[22:23], v[22:23], v[30:31]
	v_pk_mul_f32 v[24:25], v[24:25], v[32:33]
	v_pk_mul_f32 v[26:27], v[18:19], v[26:27]
	v_pk_mul_f32 v[28:29], v[20:21], v[28:29]
	v_cvt_pk_bf16_f32 v18, v22, v23
	v_cvt_pk_bf16_f32 v19, v24, v25
	v_cvt_pk_bf16_f32 v20, v26, v27
	v_cvt_pk_bf16_f32 v21, v28, v29
	global_store_dwordx4 v[34:35], v[18:21], off
	s_nop 0
	s_nop 0
	v_add_u32_e32 v20, 0x2c00, v151
	v_and_or_b32 v20, v20, s64, v152
	v_lshlrev_b32_e32 v138, 1, v20
	v_mov_b32_e32 v18, v183
	v_fmamk_f32 v18, v18, 0x39800000, v156
	v_mul_f32_e32 v19, 0x4f800000, v18
	v_cmp_gt_f32_e32 vcc, s61, v18
	s_nop 1
	v_cndmask_b32_e32 v18, v18, v19, vcc
	v_sqrt_f32_e32 v19, v18
	s_nop 0
	v_add_u32_e32 v20, -1, v19
	v_add_u32_e32 v21, 1, v19
	v_fma_f32 v22, -v20, v19, v18
	v_fma_f32 v23, -v21, v19, v18
	v_cmp_ge_f32_e64 s[4:5], 0, v22
	s_nop 1
	v_cndmask_b32_e64 v19, v19, v20, s[4:5]
	v_cmp_lt_f32_e64 s[4:5], 0, v23
	s_nop 1
	v_cndmask_b32_e64 v19, v19, v21, s[4:5]
	v_mul_f32_e32 v20, 0x37800000, v19
	v_cndmask_b32_e32 v19, v19, v20, vcc
	v_cmp_class_f32_e32 vcc, v18, v157
	s_nop 1
	v_cndmask_b32_e32 v20, v19, v18, vcc
	v_div_scale_f32 v21, s[4:5], v20, v20, 1.0
	v_rcp_f32_e32 v22, v21
	v_div_scale_f32 v23, vcc, 1.0, v20, 1.0
	v_lshl_add_u64 v[18:19], v[66:67], 0, v[138:139]
	v_fma_f32 v24, -v21, v22, 1.0
	v_fmac_f32_e32 v22, v24, v22
	v_mul_f32_e32 v24, v23, v22
	v_fma_f32 v25, -v21, v24, v23
	v_fmac_f32_e32 v24, v25, v22
	v_fma_f32 v21, -v21, v24, v23
	v_div_fmas_f32 v21, v21, v22, v24
	v_div_fixup_f32 v20, v21, v20, 1.0
	v_pk_mul_f32 v[16:17], v[16:17], v[20:21] op_sel_hi:[1,0]
	v_pk_mul_f32 v[14:15], v[14:15], v[20:21] op_sel_hi:[1,0]
	v_pk_mul_f32 v[12:13], v[12:13], v[20:21] op_sel_hi:[1,0]
	v_pk_mul_f32 v[10:11], v[10:11], v[20:21] op_sel_hi:[1,0]
	v_pk_mul_f32 v[8:9], v[8:9], v[20:21] op_sel_hi:[1,0]
	v_pk_mul_f32 v[6:7], v[6:7], v[20:21] op_sel_hi:[1,0]
	v_pk_mul_f32 v[4:5], v[4:5], v[20:21] op_sel_hi:[1,0]
	v_pk_mul_f32 v[2:3], v[2:3], v[20:21] op_sel_hi:[1,0]
	v_mul_f32_e32 v20, 0xbfb8aa3b, v14
	v_mul_f32_e32 v21, 0xbfb8aa3b, v15
	v_mul_f32_e32 v22, 0xbfb8aa3b, v16
	v_mul_f32_e32 v23, 0xbfb8aa3b, v17
	v_mul_f32_e32 v24, 0xbfb8aa3b, v10
	v_mul_f32_e32 v25, 0xbfb8aa3b, v11
	v_mul_f32_e32 v26, 0xbfb8aa3b, v12
	v_mul_f32_e32 v27, 0xbfb8aa3b, v13
	v_exp_f32_e32 v20, v20
	v_exp_f32_e32 v21, v21
	v_exp_f32_e32 v22, v22
	v_exp_f32_e32 v23, v23
	v_exp_f32_e32 v24, v24
	v_exp_f32_e32 v25, v25
	v_exp_f32_e32 v26, v26
	v_exp_f32_e32 v27, v27
	v_add_f32_e32 v20, 1.0, v20
	v_add_f32_e32 v21, 1.0, v21
	v_add_f32_e32 v22, 1.0, v22
	v_add_f32_e32 v23, 1.0, v23
	v_add_f32_e32 v24, 1.0, v24
	v_add_f32_e32 v25, 1.0, v25
	v_add_f32_e32 v26, 1.0, v26
	v_add_f32_e32 v27, 1.0, v27
	v_rcp_f32_e32 v20, v20
	v_rcp_f32_e32 v21, v21
	v_rcp_f32_e32 v22, v22
	v_rcp_f32_e32 v23, v23
	v_rcp_f32_e32 v24, v24
	v_rcp_f32_e32 v25, v25
	v_rcp_f32_e32 v26, v26
	v_rcp_f32_e32 v27, v27
	v_pk_mul_f32 v[14:15], v[14:15], v[20:21]
	v_pk_mul_f32 v[16:17], v[16:17], v[22:23]
	v_pk_mul_f32 v[10:11], v[10:11], v[24:25]
	v_pk_mul_f32 v[12:13], v[12:13], v[26:27]
	v_pk_mul_f32 v[6:7], v[6:7], v[14:15]
	v_pk_mul_f32 v[8:9], v[8:9], v[16:17]
	v_pk_mul_f32 v[10:11], v[2:3], v[10:11]
	v_pk_mul_f32 v[12:13], v[4:5], v[12:13]
	s_andn2_b64 vcc, exec, s[0:1]
	v_cvt_pk_bf16_f32 v2, v6, v7
	v_cvt_pk_bf16_f32 v3, v8, v9
	v_cvt_pk_bf16_f32 v4, v10, v11
	v_cvt_pk_bf16_f32 v5, v12, v13
	s_mov_b64 s[0:1], -1
	global_store_dwordx4 v[18:19], v[2:5], off
	s_cbranch_vccnz .LBB0_836
	s_andn2_b64 vcc, exec, s[10:11]
	s_cbranch_vccnz .LBB0_835
	s_barrier
	s_branch .LBB0_835
